# LayerNorm wave reductions: ds_bpermute butterflies replaced by DPP quad_perm/row_mirror adds and permlane16/32 swaps
# baseline (speedup 1.0000x reference)
; template <int WHICH>
; __device__ __forceinline__ void ln_phase(const Args& args, int l, const float* mod_l, hf16* H, bf16_t* MIX, const bf16_t* PART, bf16_t* XM, int lane, int gw, int NGW) {
;     ...
; #pragma unroll
;             for (int i4 = 0; i4 < 4; ++i4) { const int i = hb * 4 + i4;
; #pragma unroll
;                 for (int r = 0; r < 2; ++r) { const u32x2 w = mw[r][i4];
;                     const f32x4 mx = {__uint_as_float(w.x << 16), __uint_as_float(w.x & 0xffff0000u), __uint_as_float(w.y << 16), __uint_as_float(w.y & 0xffff0000u)};
;                     v[r][i] = hv[r][i4] * ALPHA + gt[i4] * mx; }
;                 sum0 += (v[0][i][0] + v[0][i][1]) + (v[0][i][2] + v[0][i][3]); sum1 += (v[1][i][0] + v[1][i][1]) + (v[1][i][2] + v[1][i][3]); }
.LBB0_1057:
	v_lshlrev_b32_e32 v182, 16, v172
	v_and_b32_e32 v183, 0xffff0000, v172
	v_lshlrev_b32_e32 v172, 16, v173
	v_and_b32_e32 v173, 0xffff0000, v173
	v_pk_mul_f32 v[64:65], v[64:65], s[40:41] op_sel_hi:[1,0]
	v_pk_mul_f32 v[62:63], v[62:63], s[40:41] op_sel_hi:[1,0]
	v_pk_fma_f32 v[222:223], v[84:85], v[172:173], v[64:65]
	v_pk_fma_f32 v[224:225], v[82:83], v[182:183], v[62:63]
	v_lshlrev_b32_e32 v62, 16, v170
	v_and_b32_e32 v63, 0xffff0000, v170
	v_lshlrev_b32_e32 v64, 16, v171
	v_and_b32_e32 v65, 0xffff0000, v171
	v_pk_mul_f32 v[60:61], v[60:61], s[40:41] op_sel_hi:[1,0]
	v_pk_mul_f32 v[58:59], v[58:59], s[40:41] op_sel_hi:[1,0]
	v_pk_fma_f32 v[214:215], v[84:85], v[64:65], v[60:61]
	v_pk_fma_f32 v[218:219], v[82:83], v[62:63], v[58:59]
	v_add_f32_e32 v1, v224, v225
	v_add_f32_e32 v58, v222, v223
	v_add_f32_e32 v1, v1, v58
	v_add_f32_e32 v58, v218, v219
	v_add_f32_e32 v59, v214, v215
	v_add_f32_e32 v58, v58, v59
	v_add_f32_e32 v62, 0, v58
	v_lshlrev_b32_e32 v58, 16, v168
	v_and_b32_e32 v59, 0xffff0000, v168
	v_lshlrev_b32_e32 v60, 16, v169
	v_and_b32_e32 v61, 0xffff0000, v169
	v_pk_mul_f32 v[56:57], v[56:57], s[40:41] op_sel_hi:[1,0]
	v_pk_mul_f32 v[54:55], v[54:55], s[40:41] op_sel_hi:[1,0]
	v_pk_fma_f32 v[216:217], v[76:77], v[60:61], v[56:57]
	v_pk_fma_f32 v[220:221], v[74:75], v[58:59], v[54:55]
	v_lshlrev_b32_e32 v54, 16, v166
	v_and_b32_e32 v55, 0xffff0000, v166
	v_pk_mul_f32 v[50:51], v[50:51], s[40:41] op_sel_hi:[1,0]
	v_lshlrev_b32_e32 v56, 16, v167
	v_and_b32_e32 v57, 0xffff0000, v167
	v_pk_mul_f32 v[52:53], v[52:53], s[40:41] op_sel_hi:[1,0]
	v_pk_fma_f32 v[212:213], v[74:75], v[54:55], v[50:51]
	v_add_f32_e32 v50, v220, v221
	v_add_f32_e32 v51, v216, v217
	v_add_f32_e32 v1, 0, v1
	v_pk_fma_f32 v[210:211], v[76:77], v[56:57], v[52:53]
	v_add_f32_e32 v50, v50, v51
	v_add_f32_e32 v1, v50, v1
	v_add_f32_e32 v50, v212, v213
	v_add_f32_e32 v51, v210, v211
	v_add_f32_e32 v50, v50, v51
	v_add_f32_e32 v54, v50, v62
	v_lshlrev_b32_e32 v50, 16, v164
	v_and_b32_e32 v51, 0xffff0000, v164
	v_lshlrev_b32_e32 v52, 16, v165
	v_and_b32_e32 v53, 0xffff0000, v165
	v_pk_mul_f32 v[48:49], v[48:49], s[40:41] op_sel_hi:[1,0]
	v_pk_mul_f32 v[46:47], v[46:47], s[40:41] op_sel_hi:[1,0]
	v_pk_fma_f32 v[206:207], v[72:73], v[52:53], v[48:49]
	v_pk_fma_f32 v[208:209], v[70:71], v[50:51], v[46:47]
	v_lshlrev_b32_e32 v46, 16, v162
	v_and_b32_e32 v47, 0xffff0000, v162
	v_pk_mul_f32 v[42:43], v[42:43], s[40:41] op_sel_hi:[1,0]
	v_lshlrev_b32_e32 v48, 16, v163
	v_and_b32_e32 v49, 0xffff0000, v163
	v_pk_mul_f32 v[44:45], v[44:45], s[40:41] op_sel_hi:[1,0]
	v_pk_fma_f32 v[202:203], v[70:71], v[46:47], v[42:43]
	v_add_f32_e32 v42, v208, v209
	v_add_f32_e32 v43, v206, v207
	v_pk_fma_f32 v[198:199], v[72:73], v[48:49], v[44:45]
	v_add_f32_e32 v42, v42, v43
	v_add_f32_e32 v1, v42, v1
	v_add_f32_e32 v42, v202, v203
	v_add_f32_e32 v43, v198, v199
	v_add_f32_e32 v42, v42, v43
	v_add_f32_e32 v46, v42, v54
	v_lshlrev_b32_e32 v42, 16, v160
	v_and_b32_e32 v43, 0xffff0000, v160
	v_lshlrev_b32_e32 v44, 16, v161
	v_and_b32_e32 v45, 0xffff0000, v161
	v_pk_mul_f32 v[40:41], v[40:41], s[40:41] op_sel_hi:[1,0]
	v_pk_mul_f32 v[38:39], v[38:39], s[40:41] op_sel_hi:[1,0]
	v_pk_fma_f32 v[200:201], v[68:69], v[44:45], v[40:41]
	v_pk_fma_f32 v[204:205], v[66:67], v[42:43], v[38:39]
	v_lshlrev_b32_e32 v38, 16, v158
	v_and_b32_e32 v39, 0xffff0000, v158
	v_pk_mul_f32 v[34:35], v[34:35], s[40:41] op_sel_hi:[1,0]
	v_lshlrev_b32_e32 v40, 16, v159
	v_and_b32_e32 v41, 0xffff0000, v159
	v_pk_mul_f32 v[36:37], v[36:37], s[40:41] op_sel_hi:[1,0]
	v_pk_fma_f32 v[196:197], v[66:67], v[38:39], v[34:35]
	v_add_f32_e32 v34, v204, v205
	v_add_f32_e32 v35, v200, v201
	v_pk_fma_f32 v[194:195], v[68:69], v[40:41], v[36:37]
	v_add_f32_e32 v34, v34, v35
	v_add_f32_e32 v1, v34, v1
	v_add_f32_e32 v34, v196, v197
	v_add_f32_e32 v35, v194, v195
	v_add_f32_e32 v34, v34, v35
	v_add_f32_e32 v42, v34, v46
	s_waitcnt vmcnt(10)
	v_lshlrev_b32_e32 v34, 16, v188
	v_and_b32_e32 v35, 0xffff0000, v188
	v_lshlrev_b32_e32 v36, 16, v189
	v_and_b32_e32 v37, 0xffff0000, v189
	v_pk_mul_f32 v[38:39], v[4:5], s[40:41] op_sel_hi:[1,0]
	v_pk_mul_f32 v[40:41], v[2:3], s[40:41] op_sel_hi:[1,0]
	v_pk_fma_f32 v[188:189], v[96:97], v[36:37], v[38:39]
	v_pk_fma_f32 v[192:193], v[94:95], v[34:35], v[40:41]
	s_waitcnt vmcnt(9)
	v_lshlrev_b32_e32 v34, 16, v190
	v_and_b32_e32 v35, 0xffff0000, v190
	v_lshlrev_b32_e32 v36, 16, v191
	v_and_b32_e32 v37, 0xffff0000, v191
	v_pk_mul_f32 v[38:39], v[8:9], s[40:41] op_sel_hi:[1,0]
	v_pk_mul_f32 v[40:41], v[6:7], s[40:41] op_sel_hi:[1,0]
	v_pk_fma_f32 v[164:165], v[96:97], v[36:37], v[38:39]
	v_pk_fma_f32 v[172:173], v[94:95], v[34:35], v[40:41]
	v_pk_mov_b32 v[34:35], v[192:193], v[188:189] op_sel:[1,0]
	v_mov_b32_e32 v36, v192
	v_mov_b32_e32 v37, v189
	v_pk_add_f32 v[34:35], v[34:35], v[36:37]
	v_pk_mov_b32 v[36:37], v[172:173], v[164:165] op_sel:[1,0]
	v_mov_b32_e32 v38, v172
	v_mov_b32_e32 v39, v165
	v_add_f32_e32 v34, v34, v35
	v_pk_add_f32 v[36:37], v[36:37], v[38:39]
	v_add_f32_e32 v35, v1, v34
	v_add_f32_e32 v1, v36, v37
	v_add_f32_e32 v37, v42, v1
	s_waitcnt vmcnt(7)
	v_lshlrev_b32_e32 v38, 16, v176
	v_and_b32_e32 v39, 0xffff0000, v176
	v_lshlrev_b32_e32 v40, 16, v177
	v_and_b32_e32 v41, 0xffff0000, v177
	v_pk_mul_f32 v[42:43], v[12:13], s[40:41] op_sel_hi:[1,0]
	v_pk_mul_f32 v[44:45], v[10:11], s[40:41] op_sel_hi:[1,0]
	v_pk_fma_f32 v[176:177], v[92:93], v[40:41], v[42:43]
	v_pk_fma_f32 v[190:191], v[90:91], v[38:39], v[44:45]
	s_waitcnt vmcnt(6)
; __device__ __forceinline__ float shflx(float v, int mask, int lane) { return __int_as_float(__builtin_amdgcn_ds_bpermute((lane ^ mask) << 2, __float_as_int(v))); }
; __device__ __forceinline__ float wave_sum(float v, int lane) {
; #pragma unroll
;     for (int o = 1; o < 64; o <<= 1) v += shflx(v, o, lane);
;     return v;
; template <int WHICH>
; __device__ __forceinline__ void ln_phase(const Args& args, int l, const float* mod_l, hf16* H, bf16_t* MIX, const bf16_t* PART, bf16_t* XM, int lane, int gw, int NGW) {
;     ...
; #pragma unroll
;             for (int i4 = 0; i4 < 4; ++i4) { const int i = hb * 4 + i4;
; #pragma unroll
;                 for (int r = 0; r < 2; ++r) { const u32x2 w = mw[r][i4];
;                     const f32x4 mx = {__uint_as_float(w.x << 16), __uint_as_float(w.x & 0xffff0000u), __uint_as_float(w.y << 16), __uint_as_float(w.y & 0xffff0000u)};
;                     v[r][i] = hv[r][i4] * ALPHA + gt[i4] * mx; }
;                 sum0 += (v[0][i][0] + v[0][i][1]) + (v[0][i][2] + v[0][i][3]); sum1 += (v[1][i][0] + v[1][i][1]) + (v[1][i][2] + v[1][i][3]); }
;             __builtin_amdgcn_sched_barrier(0);
;         }
;         const float mean0 = wave_sum(sum0, lane) * (1.0f / DM), mean1 = wave_sum(sum1, lane) * (1.0f / DM); float sq0 = 0.f, sq1 = 0.f;
; #pragma unroll
;         for (int i = 0; i < 8; ++i) { v[0][i] = v[0][i] - mean0; v[1][i] = v[1][i] - mean1;
	v_lshlrev_b32_e32 v38, 16, v186
	v_and_b32_e32 v39, 0xffff0000, v186
	v_lshlrev_b32_e32 v40, 16, v187
	v_and_b32_e32 v41, 0xffff0000, v187
	v_pk_mul_f32 v[42:43], v[16:17], s[40:41] op_sel_hi:[1,0]
	v_pk_mul_f32 v[44:45], v[14:15], s[40:41] op_sel_hi:[1,0]
	v_pk_fma_f32 v[166:167], v[92:93], v[40:41], v[42:43]
	v_pk_fma_f32 v[170:171], v[90:91], v[38:39], v[44:45]
	v_pk_mov_b32 v[38:39], v[190:191], v[176:177] op_sel:[1,0]
	v_mov_b32_e32 v40, v190
	v_mov_b32_e32 v41, v177
	v_pk_add_f32 v[38:39], v[38:39], v[40:41]
	v_pk_mov_b32 v[40:41], v[170:171], v[166:167] op_sel:[1,0]
	v_mov_b32_e32 v42, v170
	v_mov_b32_e32 v43, v167
	v_pk_add_f32 v[40:41], v[40:41], v[42:43]
	s_waitcnt vmcnt(4)
	v_lshlrev_b32_e32 v42, 16, v174
	v_and_b32_e32 v43, 0xffff0000, v174
	v_lshlrev_b32_e32 v44, 16, v175
	v_and_b32_e32 v45, 0xffff0000, v175
	v_pk_mul_f32 v[46:47], v[20:21], s[40:41] op_sel_hi:[1,0]
	v_pk_mul_f32 v[48:49], v[18:19], s[40:41] op_sel_hi:[1,0]
	s_waitcnt vmcnt(1)
	v_lshlrev_b32_e32 v50, 16, v228
	v_and_b32_e32 v51, 0xffff0000, v228
	v_lshlrev_b32_e32 v52, 16, v229
	v_and_b32_e32 v53, 0xffff0000, v229
	v_pk_mul_f32 v[54:55], v[28:29], s[40:41] op_sel_hi:[1,0]
	v_pk_mul_f32 v[56:57], v[26:27], s[40:41] op_sel_hi:[1,0]
	v_pk_add_f32 v[38:39], v[38:39], v[38:39] op_sel_hi:[0,1]
	v_pk_fma_f32 v[174:175], v[88:89], v[44:45], v[46:47]
	v_pk_fma_f32 v[186:187], v[86:87], v[42:43], v[48:49]
	v_lshlrev_b32_e32 v42, 16, v230
	v_and_b32_e32 v43, 0xffff0000, v230
	v_lshlrev_b32_e32 v44, 16, v231
	v_and_b32_e32 v45, 0xffff0000, v231
	v_pk_mul_f32 v[46:47], v[24:25], s[40:41] op_sel_hi:[1,0]
	v_pk_mul_f32 v[48:49], v[22:23], s[40:41] op_sel_hi:[1,0]
	v_pk_fma_f32 v[158:159], v[80:81], v[52:53], v[54:55]
	v_pk_fma_f32 v[162:163], v[78:79], v[50:51], v[56:57]
	v_pk_fma_f32 v[160:161], v[88:89], v[44:45], v[46:47]
	v_pk_fma_f32 v[168:169], v[86:87], v[42:43], v[48:49]
	v_add_f32_e32 v43, v186, v187
	v_add_f32_e32 v45, v174, v175
	s_waitcnt vmcnt(0)
	v_lshlrev_b32_e32 v50, 16, v226
	v_and_b32_e32 v51, 0xffff0000, v226
	v_lshlrev_b32_e32 v52, 16, v227
	v_and_b32_e32 v53, 0xffff0000, v227
	v_pk_mul_f32 v[54:55], v[32:33], s[40:41] op_sel_hi:[1,0]
	v_pk_mul_f32 v[56:57], v[30:31], s[40:41] op_sel_hi:[1,0]
	v_mov_b32_e32 v42, v162
	v_mov_b32_e32 v44, v163
	v_mov_b32_e32 v38, v158
	v_mov_b32_e32 v34, v159
	v_pk_add_f32 v[40:41], v[40:41], v[40:41] op_sel_hi:[0,1]
	v_pk_fma_f32 v[94:95], v[80:81], v[52:53], v[54:55]
	v_pk_fma_f32 v[96:97], v[78:79], v[50:51], v[56:57]
	v_pk_add_f32 v[42:43], v[42:43], v[44:45]
	v_pk_add_f32 v[34:35], v[38:39], v[34:35]
	v_add_f32_e32 v47, v168, v169
	v_add_f32_e32 v49, v160, v161
	v_pk_add_f32 v[34:35], v[42:43], v[34:35]
	v_mov_b32_e32 v46, v96
	v_mov_b32_e32 v48, v97
	v_mov_b32_e32 v40, v94
	v_mov_b32_e32 v36, v95
	v_add_f32_e32 v1, v34, v35
	v_pk_add_f32 v[34:35], v[46:47], v[48:49]
	v_pk_add_f32 v[36:37], v[40:41], v[36:37]
	s_nop 0
	v_pk_add_f32 v[34:35], v[34:35], v[36:37]
	s_nop 0
	v_add_f32_e32 v34, v34, v35
	s_mov_b32 s4, 0x3a000000
	s_waitcnt lgkmcnt(0)
	s_nop 1
	v_add_f32_dpp v1, v1, v1 quad_perm:[1,0,3,2] row_mask:0xf bank_mask:0xf
	s_waitcnt lgkmcnt(0)
	s_nop 1
	v_add_f32_dpp v1, v1, v1 quad_perm:[2,3,0,1] row_mask:0xf bank_mask:0xf
	s_waitcnt lgkmcnt(0)
	s_nop 1
	v_add_f32_dpp v1, v1, v1 row_half_mirror row_mask:0xf bank_mask:0xf
	s_waitcnt lgkmcnt(0)
	s_nop 1
	v_add_f32_dpp v1, v1, v1 row_mirror row_mask:0xf bank_mask:0xf
	s_waitcnt lgkmcnt(0)
	v_mov_b32_e32 v35, v1
	s_nop 1
	v_permlane16_swap_b32_e32 v1, v35
	v_add_f32_e32 v1, v1, v35
	s_waitcnt lgkmcnt(0)
	v_mov_b32_e32 v35, v1
	s_nop 1
	v_permlane32_swap_b32_e32 v1, v35
	v_add_f32_e32 v1, v1, v35
	v_fmamk_f32 v225, v1, 0xba000000, v225
	v_fmamk_f32 v221, v1, 0xba000000, v221
	v_fmamk_f32 v223, v1, 0xba000000, v223
	v_fmac_f32_e32 v224, 0xba000000, v1
	s_waitcnt lgkmcnt(0)
	s_nop 1
	v_add_f32_dpp v34, v34, v34 quad_perm:[1,0,3,2] row_mask:0xf bank_mask:0xf
	v_fmamk_f32 v217, v1, 0xba000000, v217
	v_fmac_f32_e32 v220, 0xba000000, v1
	v_mov_b32_e32 v36, v225
	v_mov_b32_e32 v37, v221
	s_waitcnt lgkmcnt(0)
	s_nop 1
	v_add_f32_dpp v34, v34, v34 quad_perm:[2,3,0,1] row_mask:0xf bank_mask:0xf
	v_fmac_f32_e32 v222, 0xba000000, v1
	v_fmac_f32_e32 v216, 0xba000000, v1
	v_pk_mul_f32 v[36:37], v[36:37], v[36:37]
	v_mov_b32_e32 v38, v223
	s_waitcnt lgkmcnt(0)
	s_nop 1
	v_add_f32_dpp v34, v34, v34 row_half_mirror row_mask:0xf bank_mask:0xf
	v_mov_b32_e32 v39, v217
	v_pk_mul_f32 v[38:39], v[38:39], v[38:39]
	v_fmamk_f32 v209, v1, 0xba000000, v209
	v_fmac_f32_e32 v208, 0xba000000, v1
	s_waitcnt lgkmcnt(0)
	s_nop 1
	v_add_f32_dpp v34, v34, v34 row_mirror row_mask:0xf bank_mask:0xf
	v_fmamk_f32 v207, v1, 0xba000000, v207
	v_fmac_f32_e32 v206, 0xba000000, v1
	v_fmac_f32_e32 v204, 0xba000000, v1
	v_fmamk_f32 v205, v1, 0xba000000, v205
	s_waitcnt lgkmcnt(0)
	v_mov_b32_e32 v35, v34
	s_nop 1
	v_permlane16_swap_b32_e32 v34, v35
	v_add_f32_e32 v34, v34, v35
	v_fmac_f32_e32 v200, 0xba000000, v1
	v_fmamk_f32 v201, v1, 0xba000000, v201
	v_fmamk_f32 v189, v1, 0xba000000, v189
	v_fmac_f32_e32 v188, 0xba000000, v1
	s_waitcnt lgkmcnt(0)
; __device__ __forceinline__ float shflx(float v, int mask, int lane) { return __int_as_float(__builtin_amdgcn_ds_bpermute((lane ^ mask) << 2, __float_as_int(v))); }
; __device__ __forceinline__ float wave_sum(float v, int lane) {
; #pragma unroll
;     for (int o = 1; o < 64; o <<= 1) v += shflx(v, o, lane);
;     return v;
; template <int WHICH>
; __device__ __forceinline__ void ln_phase(const Args& args, int l, const float* mod_l, hf16* H, bf16_t* MIX, const bf16_t* PART, bf16_t* XM, int lane, int gw, int NGW) {
;     ...
;         const float mean0 = wave_sum(sum0, lane) * (1.0f / DM), mean1 = wave_sum(sum1, lane) * (1.0f / DM); float sq0 = 0.f, sq1 = 0.f;
; #pragma unroll
;         for (int i = 0; i < 8; ++i) { v[0][i] = v[0][i] - mean0; v[1][i] = v[1][i] - mean1;
;             sq0 += (v[0][i][0] * v[0][i][0] + v[0][i][1] * v[0][i][1]) + (v[0][i][2] * v[0][i][2] + v[0][i][3] * v[0][i][3]);
;             sq1 += (v[1][i][0] * v[1][i][0] + v[1][i][1] * v[1][i][1]) + (v[1][i][2] * v[1][i][2] + v[1][i][3] * v[1][i][3]); }
;         const float rstd[2] = {rsqrtf(wave_sum(sq0, lane) * (1.0f / DM) + EPS), rsqrtf(wave_sum(sq1, lane) * (1.0f / DM) + EPS)};
	v_mov_b32_e32 v35, v34
	s_nop 1
	v_permlane32_swap_b32_e32 v34, v35
	v_add_f32_e32 v50, v34, v35
	v_mov_b32_e32 v34, v224
	v_mov_b32_e32 v35, v220
	v_fmamk_f32 v219, v50, 0xba000000, v219
	v_fmamk_f32 v213, v50, 0xba000000, v213
	v_pk_fma_f32 v[34:35], v[34:35], v[34:35], v[36:37]
	v_mov_b32_e32 v36, v222
	v_mov_b32_e32 v37, v216
	v_fmamk_f32 v215, v50, 0xba000000, v215
	v_fmac_f32_e32 v218, 0xba000000, v50
	v_fmamk_f32 v211, v50, 0xba000000, v211
	v_fmac_f32_e32 v212, 0xba000000, v50
	v_pk_fma_f32 v[36:37], v[36:37], v[36:37], v[38:39]
	v_mov_b32_e32 v38, v219
	v_mov_b32_e32 v39, v213
	v_fmac_f32_e32 v214, 0xba000000, v50
	v_fmac_f32_e32 v210, 0xba000000, v50
	v_pk_add_f32 v[34:35], v[34:35], v[36:37]
	v_mov_b32_e32 v36, v218
	v_mov_b32_e32 v37, v212
	v_pk_mul_f32 v[38:39], v[38:39], v[38:39]
	v_mov_b32_e32 v40, v215
	v_mov_b32_e32 v41, v211
	v_pk_fma_f32 v[36:37], v[36:37], v[36:37], v[38:39]
	v_mov_b32_e32 v38, v214
	v_mov_b32_e32 v39, v210
	v_pk_mul_f32 v[40:41], v[40:41], v[40:41]
	v_fmamk_f32 v203, v50, 0xba000000, v203
	v_pk_fma_f32 v[38:39], v[38:39], v[38:39], v[40:41]
	v_pk_mul_f32 v[40:41], v[208:209], v[208:209]
	v_pk_add_f32 v[36:37], v[36:37], v[38:39]
	v_pk_mul_f32 v[38:39], v[206:207], v[206:207]
	v_fmac_f32_e32 v202, 0xba000000, v50
	v_fmamk_f32 v199, v50, 0xba000000, v199
	v_fmac_f32_e32 v198, 0xba000000, v50
	v_pk_mov_b32 v[42:43], v[40:41], v[38:39] op_sel:[1,0]
	v_mov_b32_e32 v41, v39
	v_pk_add_f32 v[34:35], v[34:35], v[34:35] op_sel_hi:[0,1]
	v_pk_add_f32 v[38:39], v[42:43], v[40:41]
	v_pk_mul_f32 v[40:41], v[198:199], v[198:199]
	v_pk_mul_f32 v[42:43], v[202:203], v[202:203]
	v_mul_f32_e32 v34, v204, v204
	v_pk_mov_b32 v[44:45], v[42:43], v[40:41] op_sel:[1,0]
	v_mov_b32_e32 v43, v41
	v_pk_add_f32 v[40:41], v[44:45], v[42:43]
	v_fmac_f32_e32 v196, 0xba000000, v50
	v_pk_fma_f32 v[42:43], v[204:205], v[204:205], v[34:35] op_sel_hi:[1,1,0]
	v_mul_f32_e32 v34, v200, v200
	v_fmamk_f32 v197, v50, 0xba000000, v197
	v_fmac_f32_e32 v194, 0xba000000, v50
	v_pk_fma_f32 v[44:45], v[200:201], v[200:201], v[34:35] op_sel_hi:[1,1,0]
	v_mul_f32_e32 v34, v196, v196
	v_fmamk_f32 v195, v50, 0xba000000, v195
	v_pk_fma_f32 v[46:47], v[196:197], v[196:197], v[34:35] op_sel_hi:[1,1,0]
	v_mul_f32_e32 v34, v194, v194
	v_pk_add_f32 v[36:37], v[36:37], v[36:37] op_sel_hi:[0,1]
	v_pk_add_f32 v[38:39], v[38:39], v[38:39] op_sel_hi:[0,1]
	v_pk_add_f32 v[40:41], v[40:41], v[40:41] op_sel_hi:[0,1]
	v_pk_fma_f32 v[48:49], v[194:195], v[194:195], v[34:35] op_sel_hi:[1,1,0]
	v_fmamk_f32 v165, v50, 0xba000000, v165
	v_fmac_f32_e32 v164, 0xba000000, v50
	v_fmamk_f32 v173, v50, 0xba000000, v173
	v_fmac_f32_e32 v172, 0xba000000, v50
	v_fmamk_f32 v193, v1, 0xba000000, v193
	v_fmac_f32_e32 v192, 0xba000000, v1
	v_mul_f32_e32 v38, v188, v188
	v_mul_f32_e32 v34, v189, v189
	v_mul_f32_e32 v46, v172, v172
	v_mul_f32_e32 v48, v173, v173
	v_mul_f32_e32 v40, v164, v164
	v_mul_f32_e32 v36, v165, v165
	v_mul_f32_e32 v42, v192, v192
	v_mul_f32_e32 v44, v193, v193
	v_pk_add_f32 v[34:35], v[38:39], v[34:35]
	v_pk_add_f32 v[38:39], v[46:47], v[48:49]
	v_pk_add_f32 v[36:37], v[40:41], v[36:37]
	v_fmamk_f32 v191, v1, 0xba000000, v191
	v_fmac_f32_e32 v190, 0xba000000, v1
	v_fmamk_f32 v177, v1, 0xba000000, v177
	v_fmac_f32_e32 v176, 0xba000000, v1
	v_pk_add_f32 v[42:43], v[42:43], v[44:45]
	v_pk_add_f32 v[36:37], v[38:39], v[36:37]
	v_pk_mul_f32 v[38:39], v[176:177], v[176:177]
	v_pk_mul_f32 v[40:41], v[190:191], v[190:191]
	v_pk_add_f32 v[34:35], v[42:43], v[34:35]
	v_fmamk_f32 v171, v50, 0xba000000, v171
	v_fmac_f32_e32 v170, 0xba000000, v50
	v_fmamk_f32 v167, v50, 0xba000000, v167
	v_fmac_f32_e32 v166, 0xba000000, v50
	v_pk_mov_b32 v[42:43], v[40:41], v[38:39] op_sel:[1,0]
	v_mov_b32_e32 v41, v39
	v_pk_add_f32 v[34:35], v[34:35], v[34:35] op_sel_hi:[0,1]
	v_pk_add_f32 v[38:39], v[42:43], v[40:41]
	v_pk_mul_f32 v[40:41], v[166:167], v[166:167]
	v_pk_mul_f32 v[42:43], v[170:171], v[170:171]
	v_fmac_f32_e32 v186, 0xba000000, v1
	v_pk_mov_b32 v[44:45], v[42:43], v[40:41] op_sel:[1,0]
	v_mov_b32_e32 v43, v41
	v_fmamk_f32 v187, v1, 0xba000000, v187
	v_fmac_f32_e32 v174, 0xba000000, v1
	v_mul_f32_e32 v34, v186, v186
	v_pk_add_f32 v[40:41], v[44:45], v[42:43]
	v_fmamk_f32 v175, v1, 0xba000000, v175
	v_fmac_f32_e32 v168, 0xba000000, v50
	v_pk_fma_f32 v[42:43], v[186:187], v[186:187], v[34:35] op_sel_hi:[1,1,0]
	v_mul_f32_e32 v34, v174, v174
	v_fmamk_f32 v169, v50, 0xba000000, v169
	v_fmac_f32_e32 v160, 0xba000000, v50
	v_pk_fma_f32 v[44:45], v[174:175], v[174:175], v[34:35] op_sel_hi:[1,1,0]
	v_mul_f32_e32 v34, v168, v168
	v_fmamk_f32 v161, v50, 0xba000000, v161
	v_pk_fma_f32 v[46:47], v[168:169], v[168:169], v[34:35] op_sel_hi:[1,1,0]
	v_mul_f32_e32 v34, v160, v160
	v_pk_add_f32 v[36:37], v[36:37], v[36:37] op_sel_hi:[0,1]
	v_pk_add_f32 v[38:39], v[38:39], v[38:39] op_sel_hi:[0,1]
	v_pk_add_f32 v[40:41], v[40:41], v[40:41] op_sel_hi:[0,1]
	v_pk_fma_f32 v[48:49], v[160:161], v[160:161], v[34:35] op_sel_hi:[1,1,0]
	v_fmamk_f32 v159, v1, 0xba000000, v159
	v_fmac_f32_e32 v158, 0xba000000, v1
	v_fmamk_f32 v163, v1, 0xba000000, v163
	v_fmac_f32_e32 v162, 0xba000000, v1
	v_fmamk_f32 v95, v50, 0xba000000, v95
	v_fmac_f32_e32 v94, 0xba000000, v50
	v_fmamk_f32 v97, v50, 0xba000000, v97
	v_fmac_f32_e32 v96, 0xba000000, v50
	v_mul_f32_e32 v42, v162, v162
	v_mul_f32_e32 v44, v163, v163
	v_mul_f32_e32 v38, v158, v158
	v_mul_f32_e32 v34, v159, v159
	v_mul_f32_e32 v46, v96, v96
	v_mul_f32_e32 v48, v97, v97
	v_mul_f32_e32 v40, v94, v94
	v_mul_f32_e32 v36, v95, v95
	v_pk_add_f32 v[42:43], v[42:43], v[44:45]
	v_pk_add_f32 v[34:35], v[38:39], v[34:35]
	v_pk_add_f32 v[38:39], v[46:47], v[48:49]
	v_pk_add_f32 v[36:37], v[40:41], v[36:37]
	v_pk_add_f32 v[34:35], v[42:43], v[34:35]
	v_pk_add_f32 v[36:37], v[38:39], v[36:37]
	v_mov_b32_e32 v39, v34
	v_mov_b32_e32 v38, v36
	v_mov_b32_e32 v34, v37
	v_pk_add_f32 v[34:35], v[38:39], v[34:35]
	s_waitcnt lgkmcnt(0)
; __device__ __forceinline__ u32x2 pack_h4(f32x4 y) { const f32x2 a = {y[0], y[1]}, b = {y[2], y[3]}; u32x2 w; w.x = __builtin_bit_cast(unsigned, __builtin_convertvector(a, hf16x2)); w.y = __builtin_bit_cast(unsigned, __builtin_convertvector(b, hf16x2)); return w; }
; __device__ __forceinline__ unsigned pk2(float lo, float hi) { const f32x2_g v = {lo, hi}; return __builtin_bit_cast(unsigned, __builtin_convertvector(v, bf16x2_g)); }
; __device__ __forceinline__ float shflx(float v, int mask, int lane) { return __int_as_float(__builtin_amdgcn_ds_bpermute((lane ^ mask) << 2, __float_as_int(v))); }
; __device__ __forceinline__ float wave_sum(float v, int lane) {
; #pragma unroll
;     for (int o = 1; o < 64; o <<= 1) v += shflx(v, o, lane);
;     return v;
; template <int WHICH>
; __device__ __forceinline__ void ln_phase(const Args& args, int l, const float* mod_l, hf16* H, bf16_t* MIX, const bf16_t* PART, bf16_t* XM, int lane, int gw, int NGW) {
;     ...
;         const float rstd[2] = {rsqrtf(wave_sum(sq0, lane) * (1.0f / DM) + EPS), rsqrtf(wave_sum(sq1, lane) * (1.0f / DM) + EPS)};
; #pragma unroll
;         for (int hb = 0; hb < 2; ++hb) {
;             f32x4 g4[4], b4[4], ms[4], ma[4];
; #pragma unroll
;             for (int i4 = 0; i4 < 4; ++i4) { const int d = lane * 4 + 256 * (hb * 4 + i4);
;                 g4[i4] = *(const f32x4*)(lg + d); b4[i4] = *(const f32x4*)(lb + d); ms[i4] = (f32x4){0.f, 0.f, 0.f, 0.f}; ma[i4] = ms[i4];
;                 if (WHICH == 0) { ms[i4] = *(const f32x4*)(mr + 4 * DM + d); ma[i4] = *(const f32x4*)(mr + 3 * DM + d); }
;                 else if (l < DEPTH - 1) { const float* mn = mr + 5 * 6 * DM; ms[i4] = *(const f32x4*)(mn + DM + d); ma[i4] = *(const f32x4*)(mn + d); } }
;             __builtin_amdgcn_sched_barrier(0);
; #pragma unroll
;             for (int i4 = 0; i4 < 4; ++i4) { const int i = hb * 4 + i4, d = lane * 4 + 256 * i;
; #pragma unroll
;                 for (int r = 0; r < 2; ++r) {
;                     const f32x4 y = v[r][i] * rstd[r] * g4[i4] + b4[i4];
;                     if (WHICH == 0 || l < DEPTH - 1) { __builtin_nontemporal_store(pack_h4(y), (u32x2*)(H + (size_t)(t + r) * DM + d));
;                         const f32x4 x2 = y * (ms[i4] + 1.0f) + ma[i4]; u32x2 w; w.x = pk2(x2[0], x2[1]); w.y = pk2(x2[2], x2[3]); *(u32x2*)(XM + (size_t)(t + r) * DM + d) = w; }
	s_nop 1
	v_add_f32_dpp v34, v34, v34 quad_perm:[1,0,3,2] row_mask:0xf bank_mask:0xf
	v_add_f32_dpp v35, v35, v35 quad_perm:[1,0,3,2] row_mask:0xf bank_mask:0xf
	s_waitcnt lgkmcnt(0)
	s_nop 1
	v_add_f32_dpp v34, v34, v34 quad_perm:[2,3,0,1] row_mask:0xf bank_mask:0xf
	v_add_f32_dpp v35, v35, v35 quad_perm:[2,3,0,1] row_mask:0xf bank_mask:0xf
	s_waitcnt lgkmcnt(0)
	s_nop 1
	v_add_f32_dpp v34, v34, v34 row_half_mirror row_mask:0xf bank_mask:0xf
	v_add_f32_dpp v35, v35, v35 row_half_mirror row_mask:0xf bank_mask:0xf
	s_waitcnt lgkmcnt(0)
	s_nop 1
	v_add_f32_dpp v34, v34, v34 row_mirror row_mask:0xf bank_mask:0xf
	v_add_f32_dpp v35, v35, v35 row_mirror row_mask:0xf bank_mask:0xf
	s_waitcnt lgkmcnt(0)
	v_mov_b32_e32 v36, v34
	v_mov_b32_e32 v37, v35
	s_nop 1
	v_permlane16_swap_b32_e32 v34, v36
	v_permlane16_swap_b32_e32 v35, v37
	v_pk_add_f32 v[34:35], v[34:35], v[36:37]
	s_waitcnt lgkmcnt(0)
	v_mov_b32_e32 v36, v34
	v_mov_b32_e32 v37, v35
	s_nop 1
	v_permlane32_swap_b32_e32 v34, v36
	v_permlane32_swap_b32_e32 v35, v37
	v_pk_add_f32 v[34:35], v[34:35], v[36:37]
	s_nop 0
	v_pk_fma_f32 v[34:35], v[34:35], s[4:5], v[184:185] op_sel_hi:[1,0,0]
	s_nop 0
	v_mul_f32_e32 v1, 0x4b800000, v35
	v_cmp_gt_f32_e64 s[4:5], s85, v35
	v_cmp_gt_f32_e32 vcc, s85, v34
	s_nop 0
	v_cndmask_b32_e64 v1, v35, v1, s[4:5]
	v_rsq_f32_e32 v1, v1
	s_nop 0
	v_mul_f32_e32 v35, 0x45800000, v1
	v_cndmask_b32_e64 v228, v1, v35, s[4:5]
	v_mul_f32_e32 v1, 0x4b800000, v34
	v_cndmask_b32_e32 v1, v34, v1, vcc
	v_rsq_f32_e32 v1, v1
	s_add_u32 s4, s17, 0x8000
	s_addc_u32 s5, s30, 0
	s_add_u32 s24, s17, 0x6000
	v_mul_f32_e32 v34, 0x45800000, v1
	v_cndmask_b32_e32 v226, v1, v34, vcc
	s_addc_u32 s25, s30, 0
	global_load_dwordx4 v[78:81], v[118:119], off
	global_load_dwordx4 v[82:85], v[120:121], off
	global_load_dwordx4 v[182:185], v178, s[4:5]
	global_load_dwordx4 v[90:93], v178, s[24:25]
	global_load_dwordx4 v[70:73], v[118:119], off offset:1024
	global_load_dwordx4 v[74:77], v[120:121], off offset:1024
	global_load_dwordx4 v[86:89], v253, s[4:5]
	global_load_dwordx4 v[66:69], v253, s[24:25]
	global_load_dwordx4 v[46:49], v[118:119], off offset:2048
	global_load_dwordx4 v[50:53], v[120:121], off offset:2048
	global_load_dwordx4 v[62:65], v237, s[4:5]
	global_load_dwordx4 v[54:57], v237, s[24:25]
	global_load_dwordx4 v[38:41], v[118:119], off offset:3072
	global_load_dwordx4 v[42:45], v[120:121], off offset:3072
	global_load_dwordx4 v[58:61], v238, s[4:5]
	global_load_dwordx4 v[34:37], v238, s[24:25]
	v_pk_mul_f32 v[224:225], v[224:225], v[228:229] op_sel_hi:[1,0]
	v_pk_mul_f32 v[222:223], v[222:223], v[228:229] op_sel_hi:[1,0]
	s_waitcnt vmcnt(14)
	v_pk_fma_f32 v[224:225], v[78:79], v[224:225], v[82:83]
	v_pk_fma_f32 v[222:223], v[80:81], v[222:223], v[84:85]
	s_waitcnt vmcnt(13)
	v_pk_add_f32 v[184:185], v[184:185], 1.0 op_sel_hi:[1,0]
	v_pk_add_f32 v[182:183], v[182:183], 1.0 op_sel_hi:[1,0]
	v_cvt_pk_f16_f32 v230, v224, v225
	v_cvt_pk_f16_f32 v231, v222, v223
	global_store_dwordx2 v[156:157], v[230:231], off nt
	s_waitcnt vmcnt(13)
	v_pk_fma_f32 v[156:157], v[184:185], v[222:223], v[92:93]
	v_pk_fma_f32 v[222:223], v[182:183], v[224:225], v[90:91]
	v_pk_mul_f32 v[214:215], v[214:215], v[226:227] op_sel_hi:[1,0]
	v_cvt_pk_bf16_f32 v222, v222, v223
	v_cvt_pk_bf16_f32 v223, v156, v157
	v_lshl_add_u64 v[156:157], v[122:123], 0, s[20:21]
	global_store_dwordx2 v[156:157], v[222:223], off
	v_pk_mul_f32 v[156:157], v[218:219], v[226:227] op_sel_hi:[1,0]
	v_pk_fma_f32 v[80:81], v[80:81], v[214:215], v[84:85]
	v_pk_fma_f32 v[78:79], v[78:79], v[156:157], v[82:83]
	s_lshl_b64 s[28:29], s[22:23], 12
	v_cvt_pk_f16_f32 v82, v78, v79
	v_cvt_pk_f16_f32 v83, v80, v81
	v_lshl_add_u64 v[84:85], v[100:101], 0, s[28:29]
	v_pk_fma_f32 v[80:81], v[184:185], v[80:81], v[92:93]
	v_pk_fma_f32 v[78:79], v[182:183], v[78:79], v[90:91]
	global_store_dwordx2 v[84:85], v[82:83], off nt
	v_cvt_pk_bf16_f32 v78, v78, v79
	v_cvt_pk_bf16_f32 v79, v80, v81
	v_lshl_add_u64 v[80:81], v[122:123], 0, s[28:29]
	v_pk_mul_f32 v[82:83], v[220:221], v[228:229] op_sel_hi:[1,0]
	v_pk_mul_f32 v[84:85], v[216:217], v[228:229] op_sel_hi:[1,0]
	s_add_u32 s22, s10, s20
	global_store_dwordx2 v[80:81], v[78:79], off
	s_waitcnt vmcnt(13)
	v_pk_add_f32 v[78:79], v[88:89], 1.0 op_sel_hi:[1,0]
	v_pk_add_f32 v[80:81], v[86:87], 1.0 op_sel_hi:[1,0]
	v_pk_fma_f32 v[84:85], v[72:73], v[84:85], v[76:77]
	v_pk_fma_f32 v[82:83], v[70:71], v[82:83], v[74:75]
	s_addc_u32 s23, s11, s21
	v_cvt_pk_f16_f32 v86, v82, v83
	v_cvt_pk_f16_f32 v87, v84, v85
	s_waitcnt vmcnt(12)
	v_pk_fma_f32 v[84:85], v[78:79], v[84:85], v[68:69]
	v_pk_fma_f32 v[82:83], v[80:81], v[82:83], v[66:67]
	s_add_u32 s20, s12, s20
	v_cvt_pk_bf16_f32 v82, v82, v83
	v_cvt_pk_bf16_f32 v83, v84, v85
	s_addc_u32 s21, s13, s21
	global_store_dwordx2 v245, v[82:83], s[20:21]
	v_pk_mul_f32 v[82:83], v[212:213], v[226:227] op_sel_hi:[1,0]
	v_pk_mul_f32 v[84:85], v[210:211], v[226:227] op_sel_hi:[1,0]
	s_add_u32 s26, s10, s28
	v_pk_fma_f32 v[72:73], v[72:73], v[84:85], v[76:77]
	v_pk_fma_f32 v[70:71], v[70:71], v[82:83], v[74:75]
	s_addc_u32 s27, s11, s29
	v_pk_fma_f32 v[68:69], v[78:79], v[72:73], v[68:69]
	v_pk_fma_f32 v[66:67], v[80:81], v[70:71], v[66:67]
	s_add_u32 s50, s12, s28
	v_cvt_pk_bf16_f32 v66, v66, v67
	v_cvt_pk_bf16_f32 v67, v68, v69
	s_addc_u32 s51, s13, s29
	global_store_dwordx2 v245, v[86:87], s[22:23] nt
	global_store_dwordx2 v245, v[66:67], s[50:51]
	v_pk_mul_f32 v[66:67], v[208:209], v[228:229] op_sel_hi:[1,0]
	v_pk_mul_f32 v[68:69], v[206:207], v[228:229] op_sel_hi:[1,0]
	s_waitcnt vmcnt(12)
; __device__ __forceinline__ u32x2 pack_h4(f32x4 y) { const f32x2 a = {y[0], y[1]}, b = {y[2], y[3]}; u32x2 w; w.x = __builtin_bit_cast(unsigned, __builtin_convertvector(a, hf16x2)); w.y = __builtin_bit_cast(unsigned, __builtin_convertvector(b, hf16x2)); return w; }
; __device__ __forceinline__ unsigned pk2(float lo, float hi) { const f32x2_g v = {lo, hi}; return __builtin_bit_cast(unsigned, __builtin_convertvector(v, bf16x2_g)); }
; template <int WHICH>
; __device__ __forceinline__ void ln_phase(const Args& args, int l, const float* mod_l, hf16* H, bf16_t* MIX, const bf16_t* PART, bf16_t* XM, int lane, int gw, int NGW) {
;     ...
;         for (int hb = 0; hb < 2; ++hb) {
;             f32x4 g4[4], b4[4], ms[4], ma[4];
; #pragma unroll
;             for (int i4 = 0; i4 < 4; ++i4) { const int d = lane * 4 + 256 * (hb * 4 + i4);
;                 g4[i4] = *(const f32x4*)(lg + d); b4[i4] = *(const f32x4*)(lb + d); ms[i4] = (f32x4){0.f, 0.f, 0.f, 0.f}; ma[i4] = ms[i4];
;                 if (WHICH == 0) { ms[i4] = *(const f32x4*)(mr + 4 * DM + d); ma[i4] = *(const f32x4*)(mr + 3 * DM + d); }
;                 else if (l < DEPTH - 1) { const float* mn = mr + 5 * 6 * DM; ms[i4] = *(const f32x4*)(mn + DM + d); ma[i4] = *(const f32x4*)(mn + d); } }
;             __builtin_amdgcn_sched_barrier(0);
; #pragma unroll
;             for (int i4 = 0; i4 < 4; ++i4) { const int i = hb * 4 + i4, d = lane * 4 + 256 * i;
; #pragma unroll
;                 for (int r = 0; r < 2; ++r) {
;                     const f32x4 y = v[r][i] * rstd[r] * g4[i4] + b4[i4];
;                     if (WHICH == 0 || l < DEPTH - 1) { __builtin_nontemporal_store(pack_h4(y), (u32x2*)(H + (size_t)(t + r) * DM + d));
;                         const f32x4 x2 = y * (ms[i4] + 1.0f) + ma[i4]; u32x2 w; w.x = pk2(x2[0], x2[1]); w.y = pk2(x2[2], x2[3]); *(u32x2*)(XM + (size_t)(t + r) * DM + d) = w; }
	v_pk_add_f32 v[64:65], v[64:65], 1.0 op_sel_hi:[1,0]
	v_pk_add_f32 v[62:63], v[62:63], 1.0 op_sel_hi:[1,0]
	v_pk_fma_f32 v[68:69], v[48:49], v[68:69], v[52:53]
	v_pk_fma_f32 v[66:67], v[46:47], v[66:67], v[50:51]
	v_cvt_pk_f16_f32 v74, v70, v71
	v_cvt_pk_f16_f32 v70, v66, v67
	v_cvt_pk_f16_f32 v71, v68, v69
	s_waitcnt vmcnt(11)
	v_pk_fma_f32 v[68:69], v[64:65], v[68:69], v[56:57]
	v_pk_fma_f32 v[66:67], v[62:63], v[66:67], v[54:55]
	global_store_dwordx2 v117, v[70:71], s[22:23] nt
	v_cvt_pk_bf16_f32 v66, v66, v67
	v_cvt_pk_bf16_f32 v67, v68, v69
	global_store_dwordx2 v117, v[66:67], s[20:21]
	v_pk_mul_f32 v[66:67], v[202:203], v[226:227] op_sel_hi:[1,0]
	v_pk_mul_f32 v[68:69], v[198:199], v[226:227] op_sel_hi:[1,0]
	v_pk_fma_f32 v[46:47], v[46:47], v[66:67], v[50:51]
	v_pk_fma_f32 v[48:49], v[48:49], v[68:69], v[52:53]
	v_cvt_pk_f16_f32 v50, v46, v47
	v_cvt_pk_f16_f32 v51, v48, v49
	v_pk_fma_f32 v[48:49], v[64:65], v[48:49], v[56:57]
	v_pk_fma_f32 v[46:47], v[62:63], v[46:47], v[54:55]
	global_store_dwordx2 v117, v[50:51], s[26:27] nt
	v_cvt_pk_bf16_f32 v46, v46, v47
	v_cvt_pk_bf16_f32 v47, v48, v49
	v_pk_mul_f32 v[50:51], v[204:205], v[228:229] op_sel_hi:[1,0]
	v_pk_mul_f32 v[52:53], v[200:201], v[228:229] op_sel_hi:[1,0]
	global_store_dwordx2 v117, v[46:47], s[50:51]
	s_waitcnt vmcnt(12)
	v_pk_add_f32 v[46:47], v[60:61], 1.0 op_sel_hi:[1,0]
	v_pk_add_f32 v[48:49], v[58:59], 1.0 op_sel_hi:[1,0]
	v_pk_fma_f32 v[52:53], v[40:41], v[52:53], v[44:45]
	v_pk_fma_f32 v[50:51], v[38:39], v[50:51], v[42:43]
	v_cvt_pk_f16_f32 v55, v52, v53
	v_cvt_pk_f16_f32 v54, v50, v51
	s_waitcnt vmcnt(11)
	v_pk_fma_f32 v[52:53], v[46:47], v[52:53], v[36:37]
	v_pk_fma_f32 v[50:51], v[48:49], v[50:51], v[34:35]
	v_cvt_pk_f16_f32 v75, v72, v73
	v_cvt_pk_bf16_f32 v50, v50, v51
	v_cvt_pk_bf16_f32 v51, v52, v53
	global_store_dwordx2 v115, v[50:51], s[20:21]
	v_pk_mul_f32 v[50:51], v[196:197], v[226:227] op_sel_hi:[1,0]
	v_pk_mul_f32 v[52:53], v[194:195], v[226:227] op_sel_hi:[1,0]
	v_pk_fma_f32 v[38:39], v[38:39], v[50:51], v[42:43]
	v_pk_fma_f32 v[40:41], v[40:41], v[52:53], v[44:45]
	v_pk_fma_f32 v[34:35], v[48:49], v[38:39], v[34:35]
	v_pk_fma_f32 v[36:37], v[46:47], v[40:41], v[36:37]
	v_cvt_pk_f16_f32 v42, v38, v39
	v_cvt_pk_f16_f32 v43, v40, v41
	v_cvt_pk_bf16_f32 v34, v34, v35
	v_cvt_pk_bf16_f32 v35, v36, v37
	global_store_dwordx2 v245, v[74:75], s[26:27] nt
	global_store_dwordx2 v115, v[54:55], s[22:23] nt
	global_store_dwordx2 v115, v[42:43], s[26:27] nt
	global_store_dwordx2 v115, v[34:35], s[50:51]
	global_load_dwordx4 v[34:37], v[124:125], off
	s_nop 0
	global_load_dwordx4 v[38:41], v[126:127], off
	global_load_dwordx4 v[42:45], v249, s[4:5]
	global_load_dwordx4 v[46:49], v249, s[24:25]
	global_load_dwordx4 v[50:53], v[128:129], off
	global_load_dwordx4 v[54:57], v[130:131], off
	global_load_dwordx4 v[58:61], v250, s[4:5]
	global_load_dwordx4 v[62:65], v250, s[24:25]
	global_load_dwordx4 v[66:69], v[132:133], off
	global_load_dwordx4 v[70:73], v[134:135], off
	global_load_dwordx4 v[74:77], v251, s[4:5]
	global_load_dwordx4 v[78:81], v251, s[24:25]
	global_load_dwordx4 v[82:85], v[136:137], off
	global_load_dwordx4 v[86:89], v[138:139], off
	global_load_dwordx4 v[90:93], v252, s[4:5]
	global_load_dwordx4 v[182:185], v252, s[24:25]
	v_pk_mul_f32 v[156:157], v[192:193], v[228:229] op_sel_hi:[1,0]
	v_pk_mul_f32 v[188:189], v[188:189], v[228:229] op_sel_hi:[1,0]
	s_waitcnt vmcnt(13)
	v_pk_add_f32 v[44:45], v[44:45], 1.0 op_sel_hi:[1,0]
	v_pk_add_f32 v[42:43], v[42:43], 1.0 op_sel_hi:[1,0]
	v_pk_fma_f32 v[188:189], v[188:189], v[36:37], v[40:41]
	v_pk_fma_f32 v[156:157], v[156:157], v[34:35], v[38:39]
	v_cvt_pk_f16_f32 v193, v188, v189
	v_cvt_pk_f16_f32 v192, v156, v157
	s_waitcnt vmcnt(12)
	v_pk_fma_f32 v[188:189], v[188:189], v[44:45], v[48:49]
	v_pk_fma_f32 v[156:157], v[156:157], v[42:43], v[46:47]
	v_pk_mul_f32 v[164:165], v[164:165], v[226:227] op_sel_hi:[1,0]
	v_cvt_pk_bf16_f32 v156, v156, v157
	v_cvt_pk_bf16_f32 v157, v188, v189
	global_store_dwordx2 v248, v[156:157], s[20:21]
	v_pk_mul_f32 v[156:157], v[172:173], v[226:227] op_sel_hi:[1,0]
	v_pk_fma_f32 v[36:37], v[164:165], v[36:37], v[40:41]
	v_pk_fma_f32 v[34:35], v[156:157], v[34:35], v[38:39]
	v_cvt_pk_f16_f32 v39, v36, v37
	v_cvt_pk_f16_f32 v38, v34, v35
	v_pk_fma_f32 v[36:37], v[36:37], v[44:45], v[48:49]
	v_pk_fma_f32 v[34:35], v[34:35], v[42:43], v[46:47]
	global_store_dwordx2 v248, v[38:39], s[26:27] nt
	v_cvt_pk_bf16_f32 v34, v34, v35
	v_cvt_pk_bf16_f32 v35, v36, v37
	v_pk_mul_f32 v[38:39], v[190:191], v[228:229] op_sel_hi:[1,0]
	v_pk_mul_f32 v[40:41], v[176:177], v[228:229] op_sel_hi:[1,0]
	global_store_dwordx2 v248, v[192:193], s[22:23] nt
	global_store_dwordx2 v248, v[34:35], s[50:51]
	s_waitcnt vmcnt(13)
; __device__ __forceinline__ u32x2 pack_h4(f32x4 y) { const f32x2 a = {y[0], y[1]}, b = {y[2], y[3]}; u32x2 w; w.x = __builtin_bit_cast(unsigned, __builtin_convertvector(a, hf16x2)); w.y = __builtin_bit_cast(unsigned, __builtin_convertvector(b, hf16x2)); return w; }
; __device__ __forceinline__ unsigned pk2(float lo, float hi) { const f32x2_g v = {lo, hi}; return __builtin_bit_cast(unsigned, __builtin_convertvector(v, bf16x2_g)); }
; template <int WHICH>
; __device__ __forceinline__ void ln_phase(const Args& args, int l, const float* mod_l, hf16* H, bf16_t* MIX, const bf16_t* PART, bf16_t* XM, int lane, int gw, int NGW) {
;     ...
;         for (int hb = 0; hb < 2; ++hb) {
;             f32x4 g4[4], b4[4], ms[4], ma[4];
; #pragma unroll
;             for (int i4 = 0; i4 < 4; ++i4) { const int d = lane * 4 + 256 * (hb * 4 + i4);
;                 g4[i4] = *(const f32x4*)(lg + d); b4[i4] = *(const f32x4*)(lb + d); ms[i4] = (f32x4){0.f, 0.f, 0.f, 0.f}; ma[i4] = ms[i4];
;                 if (WHICH == 0) { ms[i4] = *(const f32x4*)(mr + 4 * DM + d); ma[i4] = *(const f32x4*)(mr + 3 * DM + d); }
;                 else if (l < DEPTH - 1) { const float* mn = mr + 5 * 6 * DM; ms[i4] = *(const f32x4*)(mn + DM + d); ma[i4] = *(const f32x4*)(mn + d); } }
;             __builtin_amdgcn_sched_barrier(0);
; #pragma unroll
;             for (int i4 = 0; i4 < 4; ++i4) { const int i = hb * 4 + i4, d = lane * 4 + 256 * i;
; #pragma unroll
;                 for (int r = 0; r < 2; ++r) {
;                     const f32x4 y = v[r][i] * rstd[r] * g4[i4] + b4[i4];
;                     if (WHICH == 0 || l < DEPTH - 1) { __builtin_nontemporal_store(pack_h4(y), (u32x2*)(H + (size_t)(t + r) * DM + d));
;                         const f32x4 x2 = y * (ms[i4] + 1.0f) + ma[i4]; u32x2 w; w.x = pk2(x2[0], x2[1]); w.y = pk2(x2[2], x2[3]); *(u32x2*)(XM + (size_t)(t + r) * DM + d) = w; }
;                     else *(f32x4*)((float*)args.in[I_OUT_] + ((size_t)b * SEQ + (j + r - CTXL)) * DM + d) = y; } }
;             __builtin_amdgcn_sched_barrier(0);
	v_pk_add_f32 v[34:35], v[60:61], 1.0 op_sel_hi:[1,0]
	v_pk_add_f32 v[36:37], v[58:59], 1.0 op_sel_hi:[1,0]
	v_pk_fma_f32 v[40:41], v[40:41], v[52:53], v[56:57]
	v_pk_fma_f32 v[38:39], v[38:39], v[50:51], v[54:55]
	v_cvt_pk_f16_f32 v43, v40, v41
	v_cvt_pk_f16_f32 v42, v38, v39
	s_waitcnt vmcnt(12)
	v_pk_fma_f32 v[40:41], v[40:41], v[34:35], v[64:65]
	v_pk_fma_f32 v[38:39], v[38:39], v[36:37], v[62:63]
	global_store_dwordx2 v247, v[42:43], s[22:23] nt
	v_cvt_pk_bf16_f32 v38, v38, v39
	v_cvt_pk_bf16_f32 v39, v40, v41
	global_store_dwordx2 v247, v[38:39], s[20:21]
	v_pk_mul_f32 v[38:39], v[170:171], v[226:227] op_sel_hi:[1,0]
	v_pk_mul_f32 v[40:41], v[166:167], v[226:227] op_sel_hi:[1,0]
	v_pk_fma_f32 v[38:39], v[38:39], v[50:51], v[54:55]
	v_pk_fma_f32 v[40:41], v[40:41], v[52:53], v[56:57]
	v_pk_fma_f32 v[36:37], v[38:39], v[36:37], v[62:63]
	v_pk_fma_f32 v[34:35], v[40:41], v[34:35], v[64:65]
	v_cvt_pk_f16_f32 v42, v38, v39
	v_cvt_pk_f16_f32 v43, v40, v41
	v_cvt_pk_bf16_f32 v36, v36, v37
	v_cvt_pk_bf16_f32 v37, v34, v35
	v_pk_mul_f32 v[38:39], v[186:187], v[228:229] op_sel_hi:[1,0]
	v_pk_mul_f32 v[40:41], v[174:175], v[228:229] op_sel_hi:[1,0]
	global_store_dwordx2 v247, v[36:37], s[50:51]
	s_waitcnt vmcnt(12)
	v_pk_add_f32 v[34:35], v[76:77], 1.0 op_sel_hi:[1,0]
	v_pk_add_f32 v[36:37], v[74:75], 1.0 op_sel_hi:[1,0]
	v_pk_fma_f32 v[40:41], v[40:41], v[68:69], v[72:73]
	v_pk_fma_f32 v[38:39], v[38:39], v[66:67], v[70:71]
	global_store_dwordx2 v247, v[42:43], s[26:27] nt
	v_cvt_pk_f16_f32 v42, v38, v39
	v_cvt_pk_f16_f32 v43, v40, v41
	s_waitcnt vmcnt(12)
	v_pk_fma_f32 v[40:41], v[40:41], v[34:35], v[80:81]
	v_pk_fma_f32 v[38:39], v[38:39], v[36:37], v[78:79]
	global_store_dwordx2 v246, v[42:43], s[22:23] nt
	v_cvt_pk_bf16_f32 v38, v38, v39
	v_cvt_pk_bf16_f32 v39, v40, v41
	global_store_dwordx2 v246, v[38:39], s[20:21]
	v_pk_mul_f32 v[38:39], v[168:169], v[226:227] op_sel_hi:[1,0]
	v_pk_mul_f32 v[40:41], v[160:161], v[226:227] op_sel_hi:[1,0]
	v_pk_fma_f32 v[38:39], v[38:39], v[66:67], v[70:71]
	v_pk_fma_f32 v[40:41], v[40:41], v[68:69], v[72:73]
	v_pk_fma_f32 v[36:37], v[38:39], v[36:37], v[78:79]
	v_pk_fma_f32 v[34:35], v[40:41], v[34:35], v[80:81]
	v_cvt_pk_f16_f32 v42, v38, v39
	v_cvt_pk_f16_f32 v43, v40, v41
	v_cvt_pk_bf16_f32 v36, v36, v37
	v_cvt_pk_bf16_f32 v37, v34, v35
	v_pk_mul_f32 v[38:39], v[162:163], v[228:229] op_sel_hi:[1,0]
	v_pk_mul_f32 v[40:41], v[158:159], v[228:229] op_sel_hi:[1,0]
	global_store_dwordx2 v246, v[36:37], s[50:51]
	s_waitcnt vmcnt(12)
	v_pk_add_f32 v[34:35], v[92:93], 1.0 op_sel_hi:[1,0]
	v_pk_add_f32 v[36:37], v[90:91], 1.0 op_sel_hi:[1,0]
	v_pk_fma_f32 v[40:41], v[40:41], v[84:85], v[88:89]
	v_pk_fma_f32 v[38:39], v[38:39], v[82:83], v[86:87]
	global_store_dwordx2 v246, v[42:43], s[26:27] nt
	v_cvt_pk_f16_f32 v42, v38, v39
	v_cvt_pk_f16_f32 v43, v40, v41
	s_waitcnt vmcnt(12)
	v_pk_fma_f32 v[40:41], v[40:41], v[34:35], v[184:185]
	v_pk_fma_f32 v[38:39], v[38:39], v[36:37], v[182:183]
	global_store_dwordx2 v244, v[42:43], s[22:23] nt
	v_cvt_pk_bf16_f32 v38, v38, v39
	v_cvt_pk_bf16_f32 v39, v40, v41
	global_store_dwordx2 v244, v[38:39], s[20:21]
	v_pk_mul_f32 v[38:39], v[96:97], v[226:227] op_sel_hi:[1,0]
	v_pk_mul_f32 v[40:41], v[94:95], v[226:227] op_sel_hi:[1,0]
	v_pk_fma_f32 v[38:39], v[38:39], v[82:83], v[86:87]
	v_pk_fma_f32 v[40:41], v[40:41], v[84:85], v[88:89]
	v_pk_fma_f32 v[36:37], v[38:39], v[36:37], v[182:183]
	v_pk_fma_f32 v[34:35], v[40:41], v[34:35], v[184:185]
	v_cvt_pk_f16_f32 v42, v38, v39
	v_cvt_pk_f16_f32 v43, v40, v41
	v_cvt_pk_bf16_f32 v36, v36, v37
	v_cvt_pk_bf16_f32 v37, v34, v35
	global_store_dwordx2 v244, v[42:43], s[26:27] nt
	global_store_dwordx2 v244, v[36:37], s[50:51]
	v_mov_b64_e32 v[64:65], v[4:5]
	v_mov_b64_e32 v[56:57], v[12:13]
	v_mov_b64_e32 v[48:49], v[20:21]
	v_mov_b64_e32 v[40:41], v[28:29]
	v_mov_b64_e32 v[60:61], v[8:9]
	v_mov_b64_e32 v[52:53], v[16:17]
	v_mov_b64_e32 v[44:45], v[24:25]
	v_mov_b64_e32 v[36:37], v[32:33]
	v_mov_b64_e32 v[62:63], v[2:3]
	v_mov_b64_e32 v[54:55], v[10:11]
	v_mov_b64_e32 v[46:47], v[18:19]
	v_mov_b64_e32 v[38:39], v[26:27]
	v_mov_b64_e32 v[58:59], v[6:7]
	v_mov_b64_e32 v[50:51], v[14:15]
	v_mov_b64_e32 v[42:43], v[22:23]
	v_mov_b64_e32 v[34:35], v[30:31]

; template <int WHICH>
; __device__ __forceinline__ void ln_phase(const Args& args, int l, const float* mod_l, hf16* H, bf16_t* MIX, const bf16_t* PART, bf16_t* XM, int lane, int gw, int NGW) {
;     ...
;     for (int tp = gw; tp < T / 2; tp += NGW) {
;         const int t = 2 * tp, b = t / TPB, j = t - b * TPB, mrow = j < CTXL ? 4 : b;
;         if (l == DEPTH - 1 && j < CTXL) continue;
;         const float* mr = mod_l + (size_t)mrow * 6 * DM; const float* gate = mr + (WHICH ? 5 : 2) * DM;
;         const bool fromin = WHICH == 0 && l == 0;
;         const float* hin = j < CTXL ? args.in[I_CTX] + ((size_t)b * CTXL + j) * DM : args.in[I_X] + ((size_t)b * SEQ + (j - CTXL)) * DM; const hf16* hh = H + (size_t)t * DM;
;         f32x4 v[2][8]; float sum0 = 0.f, sum1 = 0.f;
; #pragma unroll
;         for (int hb = 0; hb < 2; ++hb) {
;             f32x4 gt[4], hv[2][4]; u32x2 mw[2][4], hr[2][4];
;             if (fromin) {
; #pragma unroll
;                 for (int i4 = 0; i4 < 4; ++i4)
; #pragma unroll
;                     for (int r = 0; r < 2; ++r) hv[r][i4] = *(const f32x4*)(hin + (size_t)r * DM + lane * 4 + 256 * (hb * 4 + i4));
;             } else {
; #pragma unroll
;                 for (int i4 = 0; i4 < 4; ++i4)
; #pragma unroll
;                     for (int r = 0; r < 2; ++r) hr[r][i4] = __builtin_nontemporal_load((const u32x2*)(hh + (size_t)r * DM + lane * 4 + 256 * (hb * 4 + i4)));
;             }
; #pragma unroll
;             for (int i4 = 0; i4 < 4; ++i4) { const int d = lane * 4 + 256 * (hb * 4 + i4); gt[i4] = *(const f32x4*)(gate + d);
; #pragma unroll
;                 for (int r = 0; r < 2; ++r) mw[r][i4] = __builtin_nontemporal_load((const u32x2*)(MIX + (size_t)(t + r) * LDM + d)); }
;             __builtin_amdgcn_sched_barrier(0);
;             if (!fromin) {
; #pragma unroll
;                 for (int i4 = 0; i4 < 4; ++i4)
; #pragma unroll
;                     for (int r = 0; r < 2; ++r) hv[r][i4] = unpack_h4(hr[r][i4]);
;             }
; #pragma unroll
;             for (int i4 = 0; i4 < 4; ++i4) { const int i = hb * 4 + i4;
; #pragma unroll
;                 for (int r = 0; r < 2; ++r) { const u32x2 w = mw[r][i4];
;                     const f32x4 mx = {__uint_as_float(w.x << 16), __uint_as_float(w.x & 0xffff0000u), __uint_as_float(w.y << 16), __uint_as_float(w.y & 0xffff0000u)};
.LBB0_1313:
	s_mul_hi_i32 s4, s0, 0x78787879
	s_lshr_b32 s5, s4, 31
	s_ashr_i32 s4, s4, 10
	s_add_i32 s24, s4, s5
	s_mul_i32 s4, s24, 0xffffef00
	s_add_i32 s30, s16, s4
	s_cmpk_lt_i32 s30, 0x100
	s_cselect_b64 s[4:5], -1, 0
	s_and_b64 s[6:7], s[10:11], s[4:5]
	s_and_b64 vcc, exec, s[6:7]
	s_cbranch_vccnz .LBB0_1312
	s_mul_i32 s6, s24, 6
	s_and_b64 s[4:5], s[4:5], exec
	s_cselect_b32 s4, 24, s6
	s_ashr_i32 s5, s4, 31
	s_lshl_b64 s[4:5], s[4:5], 13
	s_add_u32 s21, s1, s4
	s_addc_u32 s25, s33, s5
	s_add_u32 s4, s21, 0xa000
	s_addc_u32 s5, s25, 0
	s_ashr_i32 s17, s16, 31
	s_lshl_b64 s[22:23], s[16:17], 12
	v_lshl_add_u64 v[176:177], v[56:57], 0, s[22:23]
	v_add_co_u32_e32 v4, vcc, s48, v176
	s_mul_i32 s26, s16, 0x1080
	s_add_i32 s20, s16, 1
	v_addc_co_u32_e32 v5, vcc, 0, v177, vcc
	global_load_dwordx2 v[2:3], v[176:177], off nt
	global_load_dwordx2 v[24:25], v[176:177], off offset:512 nt
	global_load_dwordx2 v[26:27], v[176:177], off offset:1024 nt
	global_load_dwordx2 v[28:29], v[176:177], off offset:1536 nt
	global_load_dwordx2 v[30:31], v[4:5], off nt
	global_load_dwordx2 v[32:33], v[4:5], off offset:512 nt
	global_load_dwordx2 v[34:35], v[4:5], off offset:1024 nt
	global_load_dwordx2 v[36:37], v[4:5], off offset:1536 nt
	v_mad_i64_i32 v[6:7], s[6:7], s16, v180, v[58:59]
	s_add_i32 s28, s26, 0x1080
	v_mad_i64_i32 v[12:13], s[6:7], s20, v180, v[58:59]
	s_mul_hi_i32 s17, s16, 0x1080
	s_add_u32 s6, s8, s26
	s_addc_u32 s7, s9, s17
	v_lshlrev_b32_e32 v215, 2, v54
	s_mul_hi_i32 s27, s20, 0x1080
	v_lshlrev_b32_e32 v1, 1, v60
	s_add_u32 s26, s8, s28
	global_load_dwordx4 v[8:11], v215, s[4:5]
	global_load_dwordx2 v[38:39], v[6:7], off nt
	v_lshlrev_b32_e32 v6, 2, v60
	global_load_dwordx2 v[40:41], v[12:13], off nt
	s_nop 0
	global_load_dwordx4 v[12:15], v6, s[4:5]
	s_addc_u32 s27, s9, s27
	global_load_dwordx2 v[42:43], v1, s[6:7] nt
	global_load_dwordx2 v[44:45], v1, s[26:27] nt
	v_lshlrev_b32_e32 v7, 2, v62
	v_lshlrev_b32_e32 v1, 1, v62
	global_load_dwordx4 v[16:19], v7, s[4:5]
	global_load_dwordx2 v[46:47], v1, s[6:7] nt
	v_lshlrev_b32_e32 v216, 2, v64
	global_load_dwordx2 v[48:49], v1, s[26:27] nt
	global_load_dwordx4 v[20:23], v216, s[4:5]
	v_lshlrev_b32_e32 v1, 1, v64
	global_load_dwordx2 v[124:125], v1, s[6:7] nt
	global_load_dwordx2 v[126:127], v1, s[26:27] nt
	s_waitcnt vmcnt(0)
	v_cvt_f32_f16_e32 v52, v2
	v_cvt_f32_f16_sdwa v53, v2 dst_sel:DWORD dst_unused:UNUSED_PAD src0_sel:WORD_1
	v_cvt_f32_f16_e32 v2, v3
	v_cvt_f32_f16_sdwa v3, v3 dst_sel:DWORD dst_unused:UNUSED_PAD src0_sel:WORD_1
	v_cvt_f32_f16_e32 v128, v30
	v_cvt_f32_f16_sdwa v129, v30 dst_sel:DWORD dst_unused:UNUSED_PAD src0_sel:WORD_1
	v_cvt_f32_f16_e32 v30, v31
	v_cvt_f32_f16_sdwa v31, v31 dst_sel:DWORD dst_unused:UNUSED_PAD src0_sel:WORD_1
	v_lshlrev_b32_e32 v50, 16, v38
	v_and_b32_e32 v51, 0xffff0000, v38
	v_lshlrev_b32_e32 v38, 16, v39
	v_and_b32_e32 v39, 0xffff0000, v39
	v_pk_mul_f32 v[38:39], v[10:11], v[38:39]
	v_cvt_f32_f16_e32 v130, v24
	v_cvt_f32_f16_sdwa v131, v24 dst_sel:DWORD dst_unused:UNUSED_PAD src0_sel:WORD_1
	v_cvt_f32_f16_e32 v24, v25
	v_cvt_f32_f16_sdwa v25, v25 dst_sel:DWORD dst_unused:UNUSED_PAD src0_sel:WORD_1
	v_pk_mul_f32 v[142:143], v[8:9], v[50:51]
	v_pk_fma_f32 v[50:51], v[2:3], s[40:41], v[38:39] op_sel_hi:[1,0,1]
	v_lshlrev_b32_e32 v2, 16, v40
	v_and_b32_e32 v3, 0xffff0000, v40
	v_lshlrev_b32_e32 v38, 16, v41
	v_and_b32_e32 v39, 0xffff0000, v41
	v_pk_mul_f32 v[2:3], v[8:9], v[2:3]
	v_pk_mul_f32 v[8:9], v[10:11], v[38:39]
	v_cvt_f32_f16_e32 v132, v32
	v_cvt_f32_f16_sdwa v133, v32 dst_sel:DWORD dst_unused:UNUSED_PAD src0_sel:WORD_1
	v_cvt_f32_f16_e32 v32, v33
	v_cvt_f32_f16_sdwa v33, v33 dst_sel:DWORD dst_unused:UNUSED_PAD src0_sel:WORD_1
	v_pk_fma_f32 v[190:191], v[30:31], s[40:41], v[8:9] op_sel_hi:[1,0,1]
	v_pk_fma_f32 v[192:193], v[128:129], s[40:41], v[2:3] op_sel_hi:[1,0,1]
	v_lshlrev_b32_e32 v2, 16, v42
	v_and_b32_e32 v3, 0xffff0000, v42
	v_lshlrev_b32_e32 v8, 16, v43
	v_and_b32_e32 v9, 0xffff0000, v43
	v_pk_mul_f32 v[8:9], v[14:15], v[8:9]
	v_pk_mul_f32 v[2:3], v[12:13], v[2:3]
	v_pk_fma_f32 v[186:187], v[24:25], s[40:41], v[8:9] op_sel_hi:[1,0,1]
	v_pk_fma_f32 v[188:189], v[130:131], s[40:41], v[2:3] op_sel_hi:[1,0,1]
	v_lshlrev_b32_e32 v2, 16, v44
	v_and_b32_e32 v3, 0xffff0000, v44
	v_lshlrev_b32_e32 v8, 16, v45
	v_and_b32_e32 v9, 0xffff0000, v45
	v_pk_fma_f32 v[52:53], v[52:53], s[40:41], v[142:143] op_sel_hi:[1,0,1]
	v_pk_mul_f32 v[8:9], v[14:15], v[8:9]
	v_pk_mul_f32 v[2:3], v[12:13], v[2:3]
	v_pk_fma_f32 v[172:173], v[32:33], s[40:41], v[8:9] op_sel_hi:[1,0,1]
	v_pk_fma_f32 v[174:175], v[132:133], s[40:41], v[2:3] op_sel_hi:[1,0,1]
	v_mov_b32_e32 v2, v52
	v_mov_b32_e32 v3, v188
	v_mov_b32_e32 v8, v53
	v_mov_b32_e32 v9, v189
	v_pk_add_f32 v[2:3], v[2:3], v[8:9]
	v_mov_b32_e32 v8, v50
	v_mov_b32_e32 v9, v186
	v_mov_b32_e32 v10, v51
	v_mov_b32_e32 v11, v187
	v_pk_add_f32 v[8:9], v[8:9], v[10:11]
	v_mov_b32_e32 v10, v193
	v_pk_add_f32 v[8:9], v[2:3], v[8:9]
	v_mov_b32_e32 v11, v175
	v_add_f32_e32 v1, 0, v8
	v_add_f32_e32 v24, v1, v9
	v_mov_b32_e32 v8, v192
	v_mov_b32_e32 v9, v174
	v_pk_add_f32 v[8:9], v[8:9], v[10:11]
	v_mov_b32_e32 v10, v190
	v_mov_b32_e32 v11, v172
	v_mov_b32_e32 v12, v191
	v_mov_b32_e32 v13, v173
	v_pk_add_f32 v[10:11], v[10:11], v[12:13]
	v_cvt_f32_f16_e32 v134, v26
	v_cvt_f32_f16_sdwa v135, v26 dst_sel:DWORD dst_unused:UNUSED_PAD src0_sel:WORD_1
	v_cvt_f32_f16_e32 v26, v27
	v_cvt_f32_f16_sdwa v27, v27 dst_sel:DWORD dst_unused:UNUSED_PAD src0_sel:WORD_1
	v_pk_add_f32 v[8:9], v[8:9], v[10:11]
	v_cvt_f32_f16_e32 v136, v34
	v_add_f32_e32 v1, 0, v8
	v_cvt_f32_f16_sdwa v137, v34 dst_sel:DWORD dst_unused:UNUSED_PAD src0_sel:WORD_1
; __device__ __forceinline__ f32x4 unpack_h4(u32x2 w) { const unsigned lo = w.x, hi = w.y; const hf16x2 ha = __builtin_bit_cast(hf16x2, lo), hb = __builtin_bit_cast(hf16x2, hi); const f32x2 a = __builtin_convertvector(ha, f32x2); const f32x2 b = __builtin_convertvector(hb, f32x2); return (f32x4){a[0], a[1], b[0], b[1]}; }
; template <int WHICH>
; __device__ __forceinline__ void ln_phase(const Args& args, int l, const float* mod_l, hf16* H, bf16_t* MIX, const bf16_t* PART, bf16_t* XM, int lane, int gw, int NGW) {
;     ...
;         for (int hb = 0; hb < 2; ++hb) {
;             f32x4 gt[4], hv[2][4]; u32x2 mw[2][4], hr[2][4];
;             if (fromin) {
; #pragma unroll
;                 for (int i4 = 0; i4 < 4; ++i4)
; #pragma unroll
;                     for (int r = 0; r < 2; ++r) hv[r][i4] = *(const f32x4*)(hin + (size_t)r * DM + lane * 4 + 256 * (hb * 4 + i4));
;             } else {
; #pragma unroll
;                 for (int i4 = 0; i4 < 4; ++i4)
; #pragma unroll
;                     for (int r = 0; r < 2; ++r) hr[r][i4] = __builtin_nontemporal_load((const u32x2*)(hh + (size_t)r * DM + lane * 4 + 256 * (hb * 4 + i4)));
;             }
; #pragma unroll
;             for (int i4 = 0; i4 < 4; ++i4) { const int d = lane * 4 + 256 * (hb * 4 + i4); gt[i4] = *(const f32x4*)(gate + d);
; #pragma unroll
;                 for (int r = 0; r < 2; ++r) mw[r][i4] = __builtin_nontemporal_load((const u32x2*)(MIX + (size_t)(t + r) * LDM + d)); }
;             __builtin_amdgcn_sched_barrier(0);
;             if (!fromin) {
; #pragma unroll
;                 for (int i4 = 0; i4 < 4; ++i4)
; #pragma unroll
;                     for (int r = 0; r < 2; ++r) hv[r][i4] = unpack_h4(hr[r][i4]);
;             }
; #pragma unroll
;             for (int i4 = 0; i4 < 4; ++i4) { const int i = hb * 4 + i4;
; #pragma unroll
;                 for (int r = 0; r < 2; ++r) { const u32x2 w = mw[r][i4];
;                     const f32x4 mx = {__uint_as_float(w.x << 16), __uint_as_float(w.x & 0xffff0000u), __uint_as_float(w.y << 16), __uint_as_float(w.y & 0xffff0000u)};
;                     v[r][i] = hv[r][i4] * ALPHA + gt[i4] * mx; }
;                 sum0 += (v[0][i][0] + v[0][i][1]) + (v[0][i][2] + v[0][i][3]); sum1 += (v[1][i][0] + v[1][i][1]) + (v[1][i][2] + v[1][i][3]); }
	v_cvt_f32_f16_e32 v34, v35
	v_cvt_f32_f16_sdwa v35, v35 dst_sel:DWORD dst_unused:UNUSED_PAD src0_sel:WORD_1
	v_add_f32_e32 v30, v1, v9
	v_lshlrev_b32_e32 v8, 16, v46
	v_and_b32_e32 v9, 0xffff0000, v46
	v_lshlrev_b32_e32 v10, 16, v47
	v_and_b32_e32 v11, 0xffff0000, v47
	v_pk_mul_f32 v[10:11], v[18:19], v[10:11]
	v_pk_mul_f32 v[8:9], v[16:17], v[8:9]
	v_pk_fma_f32 v[168:169], v[26:27], s[40:41], v[10:11] op_sel_hi:[1,0,1]
	v_pk_fma_f32 v[170:171], v[134:135], s[40:41], v[8:9] op_sel_hi:[1,0,1]
	v_lshlrev_b32_e32 v8, 16, v48
	v_and_b32_e32 v9, 0xffff0000, v48
	v_lshlrev_b32_e32 v10, 16, v49
	v_and_b32_e32 v11, 0xffff0000, v49
	v_pk_mul_f32 v[10:11], v[18:19], v[10:11]
	v_pk_mul_f32 v[8:9], v[16:17], v[8:9]
	v_pk_fma_f32 v[164:165], v[34:35], s[40:41], v[10:11] op_sel_hi:[1,0,1]
	v_pk_fma_f32 v[166:167], v[136:137], s[40:41], v[8:9] op_sel_hi:[1,0,1]
	v_pk_mov_b32 v[8:9], v[170:171], v[168:169] op_sel:[1,0]
	v_mov_b32_e32 v10, v170
	v_mov_b32_e32 v11, v169
	v_pk_add_f32 v[8:9], v[8:9], v[10:11]
	v_cvt_f32_f16_e32 v138, v28
	v_cvt_f32_f16_sdwa v139, v28 dst_sel:DWORD dst_unused:UNUSED_PAD src0_sel:WORD_1
	v_pk_add_f32 v[26:27], v[8:9], v[8:9] op_sel:[0,1] op_sel_hi:[1,0]
	v_pk_mov_b32 v[8:9], v[166:167], v[164:165] op_sel:[1,0]
	v_mov_b32_e32 v10, v166
	v_mov_b32_e32 v11, v165
	v_cvt_f32_f16_e32 v28, v29
	v_cvt_f32_f16_sdwa v29, v29 dst_sel:DWORD dst_unused:UNUSED_PAD src0_sel:WORD_1
	v_pk_add_f32 v[8:9], v[8:9], v[10:11]
	v_cvt_f32_f16_e32 v140, v36
	v_cvt_f32_f16_sdwa v141, v36 dst_sel:DWORD dst_unused:UNUSED_PAD src0_sel:WORD_1
	v_pk_add_f32 v[32:33], v[8:9], v[8:9] op_sel:[0,1] op_sel_hi:[1,0]
	v_lshlrev_b32_e32 v8, 16, v124
	v_and_b32_e32 v9, 0xffff0000, v124
	v_cvt_f32_f16_e32 v36, v37
	v_cvt_f32_f16_sdwa v37, v37 dst_sel:DWORD dst_unused:UNUSED_PAD src0_sel:WORD_1
	v_lshlrev_b32_e32 v10, 16, v125
	v_and_b32_e32 v11, 0xffff0000, v125
	v_pk_mul_f32 v[8:9], v[20:21], v[8:9]
	v_pk_mul_f32 v[10:11], v[22:23], v[10:11]
	v_pk_fma_f32 v[162:163], v[138:139], s[40:41], v[8:9] op_sel_hi:[1,0,1]
	v_lshlrev_b32_e32 v8, 16, v126
	v_and_b32_e32 v9, 0xffff0000, v126
	v_pk_fma_f32 v[160:161], v[28:29], s[40:41], v[10:11] op_sel_hi:[1,0,1]
	v_lshlrev_b32_e32 v10, 16, v127
	v_and_b32_e32 v11, 0xffff0000, v127
	v_pk_mul_f32 v[8:9], v[20:21], v[8:9]
	v_pk_mul_f32 v[10:11], v[22:23], v[10:11]
	v_pk_fma_f32 v[158:159], v[140:141], s[40:41], v[8:9] op_sel_hi:[1,0,1]
	v_mov_b32_e32 v2, 0
	v_pk_fma_f32 v[156:157], v[36:37], s[40:41], v[10:11] op_sel_hi:[1,0,1]
	v_add_f32_e32 v34, v160, v161
	v_add_f32_e32 v36, v158, v159
	v_add_f32_e32 v28, v162, v163
	v_add_f32_e32 v38, v156, v157
	global_load_dwordx2 v[40:41], v[176:177], off offset:2048 nt
	global_load_dwordx2 v[42:43], v[176:177], off offset:2560 nt
	global_load_dwordx2 v[44:45], v[176:177], off offset:3072 nt
	global_load_dwordx2 v[46:47], v[176:177], off offset:3584 nt
	global_load_dwordx2 v[48:49], v[4:5], off offset:2048 nt
	global_load_dwordx2 v[124:125], v[4:5], off offset:2560 nt
	global_load_dwordx2 v[126:127], v[4:5], off offset:3072 nt
	s_nop 0
	global_load_dwordx2 v[4:5], v[4:5], off offset:3584 nt
	v_lshlrev_b32_e32 v214, 2, v66
	v_lshlrev_b32_e32 v1, 1, v66
	global_load_dwordx4 v[8:11], v214, s[4:5]
	global_load_dwordx2 v[128:129], v1, s[6:7] nt
	v_lshlrev_b32_e32 v178, 2, v68
	global_load_dwordx2 v[130:131], v1, s[26:27] nt
	global_load_dwordx4 v[12:15], v178, s[4:5]
	v_lshlrev_b32_e32 v1, 1, v68
	global_load_dwordx2 v[132:133], v1, s[6:7] nt
	global_load_dwordx2 v[134:135], v1, s[26:27] nt
	v_lshlrev_b32_e32 v73, 2, v70
	v_lshlrev_b32_e32 v1, 1, v70
	global_load_dwordx4 v[16:19], v73, s[4:5]
	global_load_dwordx2 v[136:137], v1, s[6:7] nt
	v_lshlrev_b32_e32 v71, 2, v72
	global_load_dwordx2 v[182:183], v1, s[26:27] nt
	global_load_dwordx4 v[20:23], v71, s[4:5]
	v_lshlrev_b32_e32 v1, 1, v72
	global_load_dwordx2 v[184:185], v1, s[6:7] nt
	global_load_dwordx2 v[194:195], v1, s[26:27] nt
	s_waitcnt vmcnt(19)
	v_cvt_f32_f16_e32 v138, v40
	v_cvt_f32_f16_sdwa v139, v40 dst_sel:DWORD dst_unused:UNUSED_PAD src0_sel:WORD_1
	v_cvt_f32_f16_e32 v40, v41
	v_cvt_f32_f16_sdwa v41, v41 dst_sel:DWORD dst_unused:UNUSED_PAD src0_sel:WORD_1
	s_waitcnt vmcnt(15)
	v_cvt_f32_f16_e32 v140, v48
	v_cvt_f32_f16_sdwa v141, v48 dst_sel:DWORD dst_unused:UNUSED_PAD src0_sel:WORD_1
	v_cvt_f32_f16_e32 v48, v49
	v_cvt_f32_f16_sdwa v49, v49 dst_sel:DWORD dst_unused:UNUSED_PAD src0_sel:WORD_1
	s_waitcnt vmcnt(10)
	v_lshlrev_b32_e32 v144, 16, v128
	v_and_b32_e32 v145, 0xffff0000, v128
	v_lshlrev_b32_e32 v128, 16, v129
	v_and_b32_e32 v129, 0xffff0000, v129
	v_pk_mul_f32 v[128:129], v[10:11], v[128:129]
	v_pk_mul_f32 v[144:145], v[8:9], v[144:145]
	v_pk_fma_f32 v[152:153], v[40:41], s[40:41], v[128:129] op_sel_hi:[1,0,1]
	s_waitcnt vmcnt(9)
	v_lshlrev_b32_e32 v40, 16, v130
	v_and_b32_e32 v41, 0xffff0000, v130
	v_lshlrev_b32_e32 v128, 16, v131
	v_and_b32_e32 v129, 0xffff0000, v131
	v_pk_fma_f32 v[154:155], v[138:139], s[40:41], v[144:145] op_sel_hi:[1,0,1]
	v_pk_mul_f32 v[10:11], v[10:11], v[128:129]
	v_pk_mul_f32 v[8:9], v[8:9], v[40:41]
	v_pk_fma_f32 v[148:149], v[48:49], s[40:41], v[10:11] op_sel_hi:[1,0,1]
	v_pk_fma_f32 v[150:151], v[140:141], s[40:41], v[8:9] op_sel_hi:[1,0,1]
	v_mov_b32_e32 v25, v154
	v_mov_b32_e32 v27, v155
	v_mov_b32_e32 v29, v152
	v_mov_b32_e32 v35, v153
	v_cvt_f32_f16_e32 v142, v42
	v_cvt_f32_f16_sdwa v143, v42 dst_sel:DWORD dst_unused:UNUSED_PAD src0_sel:WORD_1
	v_cvt_f32_f16_e32 v42, v43
	v_cvt_f32_f16_sdwa v43, v43 dst_sel:DWORD dst_unused:UNUSED_PAD src0_sel:WORD_1
	v_pk_add_f32 v[8:9], v[24:25], v[26:27]
	v_pk_add_f32 v[10:11], v[28:29], v[34:35]
	v_mov_b32_e32 v31, v150
	v_mov_b32_e32 v33, v151
	v_mov_b32_e32 v37, v148
	v_mov_b32_e32 v39, v149
	v_pk_add_f32 v[8:9], v[8:9], v[10:11]
	v_pk_add_f32 v[10:11], v[30:31], v[32:33]
	v_pk_add_f32 v[24:25], v[36:37], v[38:39]
	v_cvt_f32_f16_e32 v196, v124
	v_cvt_f32_f16_sdwa v197, v124 dst_sel:DWORD dst_unused:UNUSED_PAD src0_sel:WORD_1
	v_cvt_f32_f16_e32 v124, v125
	v_cvt_f32_f16_sdwa v125, v125 dst_sel:DWORD dst_unused:UNUSED_PAD src0_sel:WORD_1
	v_pk_add_f32 v[10:11], v[10:11], v[24:25]
	s_waitcnt vmcnt(7)
; __device__ __forceinline__ float shflx(float v, int mask, int lane) { return __int_as_float(__builtin_amdgcn_ds_bpermute((lane ^ mask) << 2, __float_as_int(v))); }
; __device__ __forceinline__ float wave_sum(float v, int lane) {
; #pragma unroll
;     for (int o = 1; o < 64; o <<= 1) v += shflx(v, o, lane);
;     return v;
; template <int WHICH>
; __device__ __forceinline__ void ln_phase(const Args& args, int l, const float* mod_l, hf16* H, bf16_t* MIX, const bf16_t* PART, bf16_t* XM, int lane, int gw, int NGW) {
;     ...
; #pragma unroll
;             for (int i4 = 0; i4 < 4; ++i4) { const int i = hb * 4 + i4;
; #pragma unroll
;                 for (int r = 0; r < 2; ++r) { const u32x2 w = mw[r][i4];
;                     const f32x4 mx = {__uint_as_float(w.x << 16), __uint_as_float(w.x & 0xffff0000u), __uint_as_float(w.y << 16), __uint_as_float(w.y & 0xffff0000u)};
;                     v[r][i] = hv[r][i4] * ALPHA + gt[i4] * mx; }
;                 sum0 += (v[0][i][0] + v[0][i][1]) + (v[0][i][2] + v[0][i][3]); sum1 += (v[1][i][0] + v[1][i][1]) + (v[1][i][2] + v[1][i][3]); }
;             __builtin_amdgcn_sched_barrier(0);
;         }
;         const float mean0 = wave_sum(sum0, lane) * (1.0f / DM), mean1 = wave_sum(sum1, lane) * (1.0f / DM); float sq0 = 0.f, sq1 = 0.f;
	v_lshlrev_b32_e32 v24, 16, v132
	v_and_b32_e32 v25, 0xffff0000, v132
	v_lshlrev_b32_e32 v26, 16, v133
	v_and_b32_e32 v27, 0xffff0000, v133
	v_pk_mul_f32 v[26:27], v[14:15], v[26:27]
	v_pk_mul_f32 v[24:25], v[12:13], v[24:25]
	v_pk_fma_f32 v[144:145], v[42:43], s[40:41], v[26:27] op_sel_hi:[1,0,1]
	v_pk_fma_f32 v[146:147], v[142:143], s[40:41], v[24:25] op_sel_hi:[1,0,1]
	s_waitcnt vmcnt(6)
	v_lshlrev_b32_e32 v24, 16, v134
	v_and_b32_e32 v25, 0xffff0000, v134
	v_lshlrev_b32_e32 v26, 16, v135
	v_and_b32_e32 v27, 0xffff0000, v135
	v_pk_mul_f32 v[14:15], v[14:15], v[26:27]
	v_pk_mul_f32 v[12:13], v[12:13], v[24:25]
	v_cvt_f32_f16_e32 v198, v44
	v_cvt_f32_f16_sdwa v199, v44 dst_sel:DWORD dst_unused:UNUSED_PAD src0_sel:WORD_1
	v_cvt_f32_f16_e32 v44, v45
	v_cvt_f32_f16_sdwa v45, v45 dst_sel:DWORD dst_unused:UNUSED_PAD src0_sel:WORD_1
	v_pk_fma_f32 v[140:141], v[124:125], s[40:41], v[14:15] op_sel_hi:[1,0,1]
	v_pk_fma_f32 v[142:143], v[196:197], s[40:41], v[12:13] op_sel_hi:[1,0,1]
	v_pk_mov_b32 v[12:13], v[146:147], v[144:145] op_sel:[1,0]
	v_mov_b32_e32 v14, v146
	v_mov_b32_e32 v15, v145
	v_cvt_f32_f16_e32 v202, v46
	v_cvt_f32_f16_sdwa v203, v46 dst_sel:DWORD dst_unused:UNUSED_PAD src0_sel:WORD_1
	v_cvt_f32_f16_e32 v46, v47
	v_cvt_f32_f16_sdwa v47, v47 dst_sel:DWORD dst_unused:UNUSED_PAD src0_sel:WORD_1
	v_pk_add_f32 v[12:13], v[12:13], v[14:15]
	v_pk_mov_b32 v[14:15], v[142:143], v[140:141] op_sel:[1,0]
	v_mov_b32_e32 v24, v142
	v_mov_b32_e32 v25, v141
	v_cvt_f32_f16_e32 v200, v126
	v_cvt_f32_f16_sdwa v201, v126 dst_sel:DWORD dst_unused:UNUSED_PAD src0_sel:WORD_1
	v_cvt_f32_f16_e32 v126, v127
	v_cvt_f32_f16_sdwa v127, v127 dst_sel:DWORD dst_unused:UNUSED_PAD src0_sel:WORD_1
	v_pk_add_f32 v[14:15], v[14:15], v[24:25]
	s_waitcnt vmcnt(4)
	v_lshlrev_b32_e32 v24, 16, v136
	v_and_b32_e32 v25, 0xffff0000, v136
	v_lshlrev_b32_e32 v26, 16, v137
	v_and_b32_e32 v27, 0xffff0000, v137
	v_cvt_f32_f16_e32 v204, v4
	v_cvt_f32_f16_sdwa v205, v4 dst_sel:DWORD dst_unused:UNUSED_PAD src0_sel:WORD_1
	v_cvt_f32_f16_e32 v4, v5
	v_cvt_f32_f16_sdwa v5, v5 dst_sel:DWORD dst_unused:UNUSED_PAD src0_sel:WORD_1
	v_pk_mul_f32 v[26:27], v[18:19], v[26:27]
	v_pk_mul_f32 v[24:25], v[16:17], v[24:25]
	s_waitcnt vmcnt(1)
	v_lshlrev_b32_e32 v28, 16, v184
	v_and_b32_e32 v29, 0xffff0000, v184
	v_lshlrev_b32_e32 v30, 16, v185
	v_and_b32_e32 v31, 0xffff0000, v185
	v_pk_fma_f32 v[136:137], v[44:45], s[40:41], v[26:27] op_sel_hi:[1,0,1]
	v_pk_fma_f32 v[138:139], v[198:199], s[40:41], v[24:25] op_sel_hi:[1,0,1]
	v_lshlrev_b32_e32 v24, 16, v182
	v_and_b32_e32 v25, 0xffff0000, v182
	v_lshlrev_b32_e32 v26, 16, v183
	v_and_b32_e32 v27, 0xffff0000, v183
	v_pk_mul_f32 v[30:31], v[22:23], v[30:31]
	v_pk_mul_f32 v[28:29], v[20:21], v[28:29]
	v_pk_add_f32 v[8:9], v[8:9], v[8:9] op_sel:[0,1] op_sel_hi:[1,0]
	v_pk_add_f32 v[12:13], v[12:13], v[12:13] op_sel:[0,1] op_sel_hi:[1,0]
	v_pk_mul_f32 v[18:19], v[18:19], v[26:27]
	v_pk_mul_f32 v[16:17], v[16:17], v[24:25]
	v_pk_fma_f32 v[128:129], v[46:47], s[40:41], v[30:31] op_sel_hi:[1,0,1]
	v_pk_fma_f32 v[130:131], v[202:203], s[40:41], v[28:29] op_sel_hi:[1,0,1]
	s_waitcnt vmcnt(0)
	v_lshlrev_b32_e32 v28, 16, v194
	v_and_b32_e32 v29, 0xffff0000, v194
	v_lshlrev_b32_e32 v30, 16, v195
	v_and_b32_e32 v31, 0xffff0000, v195
	v_pk_fma_f32 v[132:133], v[126:127], s[40:41], v[18:19] op_sel_hi:[1,0,1]
	v_pk_fma_f32 v[134:135], v[200:201], s[40:41], v[16:17] op_sel_hi:[1,0,1]
	v_add_f32_e32 v16, v138, v139
	v_add_f32_e32 v18, v136, v137
	v_pk_mul_f32 v[22:23], v[22:23], v[30:31]
	v_pk_mul_f32 v[20:21], v[20:21], v[28:29]
	v_mov_b32_e32 v9, v130
	v_mov_b32_e32 v13, v131
	v_mov_b32_e32 v17, v128
	v_mov_b32_e32 v19, v129
	v_pk_add_f32 v[10:11], v[10:11], v[10:11] op_sel:[0,1] op_sel_hi:[1,0]
	v_pk_add_f32 v[14:15], v[14:15], v[14:15] op_sel:[0,1] op_sel_hi:[1,0]
	v_pk_fma_f32 v[124:125], v[4:5], s[40:41], v[22:23] op_sel_hi:[1,0,1]
	v_pk_fma_f32 v[126:127], v[204:205], s[40:41], v[20:21] op_sel_hi:[1,0,1]
	v_pk_add_f32 v[4:5], v[8:9], v[12:13]
	v_pk_add_f32 v[8:9], v[16:17], v[18:19]
	v_add_f32_e32 v24, v134, v135
	v_add_f32_e32 v26, v132, v133
	v_pk_add_f32 v[4:5], v[4:5], v[8:9]
	v_mov_b32_e32 v11, v126
	v_mov_b32_e32 v15, v127
	v_mov_b32_e32 v25, v124
	v_mov_b32_e32 v27, v125
	v_add_f32_e32 v1, v4, v5
	v_pk_add_f32 v[4:5], v[10:11], v[14:15]
	v_pk_add_f32 v[8:9], v[24:25], v[26:27]
	s_nop 0
	v_pk_add_f32 v[4:5], v[4:5], v[8:9]
	s_nop 0
	v_add_f32_e32 v3, v4, v5
	global_load_dwordx4 v[30:33], v[74:75], off
	global_load_dwordx4 v[34:37], v[76:77], off
	s_add_u32 s26, s21, 0x3c000
	s_addc_u32 s27, s25, 0
	s_add_u32 s50, s21, 0x3e000
	s_waitcnt lgkmcnt(0)
	s_nop 1
	v_add_f32_dpp v1, v1, v1 quad_perm:[1,0,3,2] row_mask:0xf bank_mask:0xf
	v_mov_b32_e32 v206, 1.0
	s_addc_u32 s51, s25, 0
	s_andn2_b64 vcc, exec, s[12:13]
	v_mov_b32_e32 v210, 1.0
	s_waitcnt lgkmcnt(0)
	s_nop 1
	v_add_f32_dpp v1, v1, v1 quad_perm:[2,3,0,1] row_mask:0xf bank_mask:0xf
	v_mov_b32_e32 v211, v206
	v_mov_b32_e32 v212, 1.0
	v_mov_b32_e32 v213, 1.0
	v_mov_b32_e32 v46, 0
	s_waitcnt lgkmcnt(0)
	s_nop 1
	v_add_f32_dpp v1, v1, v1 row_half_mirror row_mask:0xf bank_mask:0xf
	v_mov_b32_e32 v47, v2
	v_mov_b32_e32 v48, 0
	v_mov_b32_e32 v49, 0
	s_waitcnt lgkmcnt(0)
	s_nop 1
	v_add_f32_dpp v1, v1, v1 row_mirror row_mask:0xf bank_mask:0xf
	s_waitcnt lgkmcnt(0)
	v_mov_b32_e32 v4, v1
	s_nop 1
	v_permlane16_swap_b32_e32 v1, v4
	v_add_f32_e32 v1, v1, v4
	s_waitcnt lgkmcnt(0)
	v_mov_b32_e32 v4, v1
	s_nop 1
	v_permlane32_swap_b32_e32 v1, v4
	v_add_f32_e32 v1, v1, v4
	v_fmamk_f32 v53, v1, 0xba000000, v53
	v_fmamk_f32 v189, v1, 0xba000000, v189
	v_fmamk_f32 v51, v1, 0xba000000, v51
	v_fmac_f32_e32 v52, 0xba000000, v1
	s_waitcnt lgkmcnt(0)
; __device__ __forceinline__ float shflx(float v, int mask, int lane) { return __int_as_float(__builtin_amdgcn_ds_bpermute((lane ^ mask) << 2, __float_as_int(v))); }
; __device__ __forceinline__ float wave_sum(float v, int lane) {
; #pragma unroll
;     for (int o = 1; o < 64; o <<= 1) v += shflx(v, o, lane);
;     return v;
; template <int WHICH>
; __device__ __forceinline__ void ln_phase(const Args& args, int l, const float* mod_l, hf16* H, bf16_t* MIX, const bf16_t* PART, bf16_t* XM, int lane, int gw, int NGW) {
;     ...
;         const float mean0 = wave_sum(sum0, lane) * (1.0f / DM), mean1 = wave_sum(sum1, lane) * (1.0f / DM); float sq0 = 0.f, sq1 = 0.f;
; #pragma unroll
;         for (int i = 0; i < 8; ++i) { v[0][i] = v[0][i] - mean0; v[1][i] = v[1][i] - mean1;
	s_nop 1
	v_add_f32_dpp v3, v3, v3 quad_perm:[1,0,3,2] row_mask:0xf bank_mask:0xf
	v_fmamk_f32 v187, v1, 0xba000000, v187
	v_fmac_f32_e32 v188, 0xba000000, v1
	v_mov_b32_e32 v8, v53
	v_mov_b32_e32 v9, v189
	s_waitcnt lgkmcnt(0)
	s_nop 1
	v_add_f32_dpp v3, v3, v3 quad_perm:[2,3,0,1] row_mask:0xf bank_mask:0xf
	v_fmac_f32_e32 v50, 0xba000000, v1
	v_fmac_f32_e32 v186, 0xba000000, v1
	v_mov_b32_e32 v5, v188
	v_pk_mul_f32 v[8:9], v[8:9], v[8:9]
	s_waitcnt lgkmcnt(0)
	s_nop 1
	v_add_f32_dpp v3, v3, v3 row_half_mirror row_mask:0xf bank_mask:0xf
	v_mov_b32_e32 v10, v51
	v_mov_b32_e32 v11, v187
	v_pk_mul_f32 v[10:11], v[10:11], v[10:11]
	v_fmamk_f32 v169, v1, 0xba000000, v169
	s_waitcnt lgkmcnt(0)
	s_nop 1
	v_add_f32_dpp v3, v3, v3 row_mirror row_mask:0xf bank_mask:0xf
	v_fmac_f32_e32 v168, 0xba000000, v1
	v_fmamk_f32 v171, v1, 0xba000000, v171
	v_fmac_f32_e32 v170, 0xba000000, v1
	v_fmac_f32_e32 v162, 0xba000000, v1
	s_waitcnt lgkmcnt(0)
	v_mov_b32_e32 v4, v3
	s_nop 1
	v_permlane16_swap_b32_e32 v3, v4
	v_add_f32_e32 v3, v3, v4
	v_fmac_f32_e32 v160, 0xba000000, v1
	v_fmamk_f32 v163, v1, 0xba000000, v163
	v_fmamk_f32 v161, v1, 0xba000000, v161
	v_fmamk_f32 v153, v1, 0xba000000, v153
	s_waitcnt lgkmcnt(0)
; __device__ __forceinline__ float shflx(float v, int mask, int lane) { return __int_as_float(__builtin_amdgcn_ds_bpermute((lane ^ mask) << 2, __float_as_int(v))); }
; __device__ __forceinline__ float wave_sum(float v, int lane) {
; #pragma unroll
;     for (int o = 1; o < 64; o <<= 1) v += shflx(v, o, lane);
;     return v;
; template <int WHICH>
; __device__ __forceinline__ void ln_phase(const Args& args, int l, const float* mod_l, hf16* H, bf16_t* MIX, const bf16_t* PART, bf16_t* XM, int lane, int gw, int NGW) {
;     ...
;         const float mean0 = wave_sum(sum0, lane) * (1.0f / DM), mean1 = wave_sum(sum1, lane) * (1.0f / DM); float sq0 = 0.f, sq1 = 0.f;
; #pragma unroll
;         for (int i = 0; i < 8; ++i) { v[0][i] = v[0][i] - mean0; v[1][i] = v[1][i] - mean1;
;             sq0 += (v[0][i][0] * v[0][i][0] + v[0][i][1] * v[0][i][1]) + (v[0][i][2] * v[0][i][2] + v[0][i][3] * v[0][i][3]);
;             sq1 += (v[1][i][0] * v[1][i][0] + v[1][i][1] * v[1][i][1]) + (v[1][i][2] * v[1][i][2] + v[1][i][3] * v[1][i][3]); }
;         const float rstd[2] = {rsqrtf(wave_sum(sq0, lane) * (1.0f / DM) + EPS), rsqrtf(wave_sum(sq1, lane) * (1.0f / DM) + EPS)};
	v_mov_b32_e32 v4, v3
	s_nop 1
	v_permlane32_swap_b32_e32 v3, v4
	v_add_f32_e32 v3, v3, v4
	v_mov_b32_e32 v4, v52
	v_fmamk_f32 v193, v3, 0xba000000, v193
	v_fmamk_f32 v175, v3, 0xba000000, v175
	v_pk_fma_f32 v[4:5], v[4:5], v[4:5], v[8:9]
	v_mov_b32_e32 v8, v50
	v_mov_b32_e32 v9, v186
	v_fmamk_f32 v191, v3, 0xba000000, v191
	v_fmac_f32_e32 v192, 0xba000000, v3
	v_fmamk_f32 v173, v3, 0xba000000, v173
	v_fmac_f32_e32 v174, 0xba000000, v3
	v_pk_fma_f32 v[8:9], v[8:9], v[8:9], v[10:11]
	v_mov_b32_e32 v10, v193
	v_mov_b32_e32 v11, v175
	v_fmac_f32_e32 v190, 0xba000000, v3
	v_fmac_f32_e32 v172, 0xba000000, v3
	v_pk_add_f32 v[4:5], v[4:5], v[8:9]
	v_mov_b32_e32 v8, v192
	v_mov_b32_e32 v9, v174
	v_pk_mul_f32 v[10:11], v[10:11], v[10:11]
	v_mov_b32_e32 v12, v191
	v_mov_b32_e32 v13, v173
	v_pk_fma_f32 v[8:9], v[8:9], v[8:9], v[10:11]
	v_mov_b32_e32 v10, v190
	v_mov_b32_e32 v11, v172
	v_pk_mul_f32 v[12:13], v[12:13], v[12:13]
	v_fmamk_f32 v165, v3, 0xba000000, v165
	v_pk_fma_f32 v[10:11], v[10:11], v[10:11], v[12:13]
	v_pk_mul_f32 v[12:13], v[170:171], v[170:171]
	v_pk_add_f32 v[8:9], v[8:9], v[10:11]
	v_pk_mul_f32 v[10:11], v[168:169], v[168:169]
	v_fmac_f32_e32 v164, 0xba000000, v3
	v_fmamk_f32 v167, v3, 0xba000000, v167
	v_fmac_f32_e32 v166, 0xba000000, v3
	v_pk_mov_b32 v[14:15], v[12:13], v[10:11] op_sel:[1,0]
	v_mov_b32_e32 v13, v11
	v_pk_add_f32 v[4:5], v[4:5], v[4:5] op_sel_hi:[0,1]
	v_pk_add_f32 v[10:11], v[14:15], v[12:13]
	v_pk_mul_f32 v[12:13], v[164:165], v[164:165]
	v_pk_mul_f32 v[14:15], v[166:167], v[166:167]
	v_mul_f32_e32 v4, v162, v162
	v_pk_mov_b32 v[16:17], v[14:15], v[12:13] op_sel:[1,0]
	v_mov_b32_e32 v15, v13
	v_pk_add_f32 v[12:13], v[16:17], v[14:15]
	v_fmac_f32_e32 v158, 0xba000000, v3
	v_pk_fma_f32 v[14:15], v[162:163], v[162:163], v[4:5] op_sel_hi:[1,1,0]
	v_mul_f32_e32 v4, v160, v160
	v_fmac_f32_e32 v156, 0xba000000, v3
	v_fmamk_f32 v159, v3, 0xba000000, v159
	v_pk_fma_f32 v[16:17], v[160:161], v[160:161], v[4:5] op_sel_hi:[1,1,0]
	v_mul_f32_e32 v4, v158, v158
	v_fmamk_f32 v157, v3, 0xba000000, v157
	v_pk_fma_f32 v[18:19], v[158:159], v[158:159], v[4:5] op_sel_hi:[1,1,0]
	v_mul_f32_e32 v4, v156, v156
	v_pk_add_f32 v[8:9], v[8:9], v[8:9] op_sel_hi:[0,1]
	v_pk_add_f32 v[10:11], v[10:11], v[10:11] op_sel_hi:[0,1]
	v_pk_add_f32 v[12:13], v[12:13], v[12:13] op_sel_hi:[0,1]
	v_pk_fma_f32 v[20:21], v[156:157], v[156:157], v[4:5] op_sel_hi:[1,1,0]
	v_fmac_f32_e32 v152, 0xba000000, v1
	v_fmamk_f32 v149, v3, 0xba000000, v149
	v_fmac_f32_e32 v148, 0xba000000, v3
	v_fmamk_f32 v151, v3, 0xba000000, v151
	v_fmac_f32_e32 v150, 0xba000000, v3
	v_fmamk_f32 v155, v1, 0xba000000, v155
	v_fmac_f32_e32 v154, 0xba000000, v1
	v_mul_f32_e32 v10, v152, v152
	v_mul_f32_e32 v4, v153, v153
	v_mul_f32_e32 v18, v150, v150
	v_mul_f32_e32 v20, v151, v151
	v_mul_f32_e32 v12, v148, v148
	v_mul_f32_e32 v8, v149, v149
	v_mul_f32_e32 v14, v154, v154
	v_mul_f32_e32 v16, v155, v155
	v_pk_add_f32 v[4:5], v[10:11], v[4:5]
	v_pk_add_f32 v[10:11], v[18:19], v[20:21]
	v_pk_add_f32 v[8:9], v[12:13], v[8:9]
	v_fmamk_f32 v145, v1, 0xba000000, v145
	v_fmac_f32_e32 v144, 0xba000000, v1
	v_fmamk_f32 v147, v1, 0xba000000, v147
	v_fmac_f32_e32 v146, 0xba000000, v1
	v_pk_add_f32 v[14:15], v[14:15], v[16:17]
	v_pk_add_f32 v[8:9], v[10:11], v[8:9]
	v_pk_mul_f32 v[10:11], v[144:145], v[144:145]
	v_pk_mul_f32 v[12:13], v[146:147], v[146:147]
	v_pk_add_f32 v[4:5], v[14:15], v[4:5]
	v_fmamk_f32 v141, v3, 0xba000000, v141
	v_fmac_f32_e32 v140, 0xba000000, v3
	v_fmamk_f32 v143, v3, 0xba000000, v143
	v_fmac_f32_e32 v142, 0xba000000, v3
	v_pk_mov_b32 v[14:15], v[12:13], v[10:11] op_sel:[1,0]
	v_mov_b32_e32 v13, v11
	v_pk_add_f32 v[4:5], v[4:5], v[4:5] op_sel_hi:[0,1]
	v_pk_add_f32 v[10:11], v[14:15], v[12:13]
	v_pk_mul_f32 v[12:13], v[140:141], v[140:141]
	v_pk_mul_f32 v[14:15], v[142:143], v[142:143]
	v_fmac_f32_e32 v138, 0xba000000, v1
	v_pk_mov_b32 v[16:17], v[14:15], v[12:13] op_sel:[1,0]
	v_mov_b32_e32 v15, v13
	v_fmac_f32_e32 v136, 0xba000000, v1
	v_fmamk_f32 v139, v1, 0xba000000, v139
	v_mul_f32_e32 v4, v138, v138
	v_pk_add_f32 v[12:13], v[16:17], v[14:15]
	v_fmamk_f32 v137, v1, 0xba000000, v137
	v_fmac_f32_e32 v134, 0xba000000, v3
	v_pk_fma_f32 v[14:15], v[138:139], v[138:139], v[4:5] op_sel_hi:[1,1,0]
	v_mul_f32_e32 v4, v136, v136
	v_fmac_f32_e32 v132, 0xba000000, v3
	v_fmamk_f32 v135, v3, 0xba000000, v135
	v_pk_fma_f32 v[16:17], v[136:137], v[136:137], v[4:5] op_sel_hi:[1,1,0]
	v_mul_f32_e32 v4, v134, v134
	v_fmamk_f32 v133, v3, 0xba000000, v133
	v_pk_fma_f32 v[18:19], v[134:135], v[134:135], v[4:5] op_sel_hi:[1,1,0]
	v_mul_f32_e32 v4, v132, v132
	v_pk_add_f32 v[8:9], v[8:9], v[8:9] op_sel_hi:[0,1]
	v_pk_add_f32 v[10:11], v[10:11], v[10:11] op_sel_hi:[0,1]
	v_pk_add_f32 v[12:13], v[12:13], v[12:13] op_sel_hi:[0,1]
	v_pk_fma_f32 v[20:21], v[132:133], v[132:133], v[4:5] op_sel_hi:[1,1,0]
	v_fmamk_f32 v129, v1, 0xba000000, v129
	v_fmac_f32_e32 v128, 0xba000000, v1
	v_fmamk_f32 v131, v1, 0xba000000, v131
	v_fmac_f32_e32 v130, 0xba000000, v1
	v_fmamk_f32 v125, v3, 0xba000000, v125
	v_fmac_f32_e32 v124, 0xba000000, v3
	v_fmamk_f32 v127, v3, 0xba000000, v127
	v_fmac_f32_e32 v126, 0xba000000, v3
	v_mul_f32_e32 v14, v130, v130
	v_mul_f32_e32 v16, v131, v131
	v_mul_f32_e32 v10, v128, v128
	v_mul_f32_e32 v4, v129, v129
	v_mul_f32_e32 v18, v126, v126
	v_mul_f32_e32 v20, v127, v127
	v_mul_f32_e32 v12, v124, v124
	v_mul_f32_e32 v8, v125, v125
	v_pk_add_f32 v[14:15], v[14:15], v[16:17]
	v_pk_add_f32 v[4:5], v[10:11], v[4:5]
	v_pk_add_f32 v[10:11], v[18:19], v[20:21]
	v_pk_add_f32 v[8:9], v[12:13], v[8:9]
	v_pk_add_f32 v[4:5], v[14:15], v[4:5]
	v_pk_add_f32 v[8:9], v[10:11], v[8:9]
	v_mov_b32_e32 v11, v4
	v_mov_b32_e32 v10, v8
	v_mov_b32_e32 v4, v9
	v_pk_add_f32 v[4:5], v[10:11], v[4:5]
	v_cndmask_b32_e64 v1, 0, 1, s[12:13]
	v_cmp_ne_u32_e64 s[4:5], 1, v1
	s_waitcnt lgkmcnt(0)
	s_nop 1
	v_add_f32_dpp v4, v4, v4 quad_perm:[1,0,3,2] row_mask:0xf bank_mask:0xf
	v_add_f32_dpp v5, v5, v5 quad_perm:[1,0,3,2] row_mask:0xf bank_mask:0xf
	s_waitcnt lgkmcnt(0)
	s_nop 1
	v_add_f32_dpp v4, v4, v4 quad_perm:[2,3,0,1] row_mask:0xf bank_mask:0xf
	v_add_f32_dpp v5, v5, v5 quad_perm:[2,3,0,1] row_mask:0xf bank_mask:0xf
	s_waitcnt lgkmcnt(0)
	s_nop 1
	v_add_f32_dpp v4, v4, v4 row_half_mirror row_mask:0xf bank_mask:0xf
	v_add_f32_dpp v5, v5, v5 row_half_mirror row_mask:0xf bank_mask:0xf
	s_waitcnt lgkmcnt(0)
	s_nop 1
	v_add_f32_dpp v4, v4, v4 row_mirror row_mask:0xf bank_mask:0xf
	v_add_f32_dpp v5, v5, v5 row_mirror row_mask:0xf bank_mask:0xf
	s_waitcnt lgkmcnt(0)
	v_mov_b32_e32 v8, v4
	v_mov_b32_e32 v9, v5
	s_nop 1
	v_permlane16_swap_b32_e32 v4, v8
	v_permlane16_swap_b32_e32 v5, v9
	v_pk_add_f32 v[194:195], v[4:5], v[8:9]
	s_cbranch_vccnz .LBB0_1316
	global_load_dwordx4 v[8:11], v215, s[50:51]
	global_load_dwordx4 v[46:49], v215, s[26:27]
	s_waitcnt vmcnt(1)
	v_pk_add_f32 v[212:213], v[10:11], 1.0 op_sel_hi:[1,0]
	v_pk_add_f32 v[210:211], v[8:9], 1.0 op_sel_hi:[1,0]

; __device__ __forceinline__ u32x2 pack_h4(f32x4 y) { const f32x2 a = {y[0], y[1]}, b = {y[2], y[3]}; u32x2 w; w.x = __builtin_bit_cast(unsigned, __builtin_convertvector(a, hf16x2)); w.y = __builtin_bit_cast(unsigned, __builtin_convertvector(b, hf16x2)); return w; }
; __device__ __forceinline__ unsigned pk2(float lo, float hi) { const f32x2_g v = {lo, hi}; return __builtin_bit_cast(unsigned, __builtin_convertvector(v, bf16x2_g)); }
; template <int WHICH>
; __device__ __forceinline__ void ln_phase(const Args& args, int l, const float* mod_l, hf16* H, bf16_t* MIX, const bf16_t* PART, bf16_t* XM, int lane, int gw, int NGW) {
;     ...
;         const float rstd[2] = {rsqrtf(wave_sum(sq0, lane) * (1.0f / DM) + EPS), rsqrtf(wave_sum(sq1, lane) * (1.0f / DM) + EPS)};
; #pragma unroll
;         for (int hb = 0; hb < 2; ++hb) {
;             f32x4 g4[4], b4[4], ms[4], ma[4];
; #pragma unroll
;             for (int i4 = 0; i4 < 4; ++i4) { const int d = lane * 4 + 256 * (hb * 4 + i4);
;                 g4[i4] = *(const f32x4*)(lg + d); b4[i4] = *(const f32x4*)(lb + d); ms[i4] = (f32x4){0.f, 0.f, 0.f, 0.f}; ma[i4] = ms[i4];
;                 if (WHICH == 0) { ms[i4] = *(const f32x4*)(mr + 4 * DM + d); ma[i4] = *(const f32x4*)(mr + 3 * DM + d); }
;                 else if (l < DEPTH - 1) { const float* mn = mr + 5 * 6 * DM; ms[i4] = *(const f32x4*)(mn + DM + d); ma[i4] = *(const f32x4*)(mn + d); } }
;             __builtin_amdgcn_sched_barrier(0);
; #pragma unroll
;             for (int i4 = 0; i4 < 4; ++i4) { const int i = hb * 4 + i4, d = lane * 4 + 256 * i;
; #pragma unroll
;                 for (int r = 0; r < 2; ++r) {
;                     const f32x4 y = v[r][i] * rstd[r] * g4[i4] + b4[i4];
;                     if (WHICH == 0 || l < DEPTH - 1) { __builtin_nontemporal_store(pack_h4(y), (u32x2*)(H + (size_t)(t + r) * DM + d));
;                         const f32x4 x2 = y * (ms[i4] + 1.0f) + ma[i4]; u32x2 w; w.x = pk2(x2[0], x2[1]); w.y = pk2(x2[2], x2[3]); *(u32x2*)(XM + (size_t)(t + r) * DM + d) = w; }
.LBB0_1322:
	s_waitcnt lgkmcnt(0)
	v_mov_b32_e32 v198, v194
	v_mov_b32_e32 v199, v195
	s_nop 1
	v_permlane32_swap_b32_e32 v194, v198
	v_permlane32_swap_b32_e32 v195, v199
	v_pk_add_f32 v[182:183], v[194:195], v[198:199]
	s_mov_b32 s6, 0x3a000000
	v_pk_fma_f32 v[198:199], v[182:183], s[6:7], v[230:231] op_sel_hi:[1,0,0]
	s_nop 0
	v_mul_f32_e32 v1, 0x4b800000, v199
	v_cmp_gt_f32_e32 vcc, s85, v199
	v_cmp_gt_f32_e64 s[6:7], s85, v198
	s_nop 0
	v_cndmask_b32_e32 v1, v199, v1, vcc
	v_rsq_f32_e32 v1, v1
	s_nop 0
	v_mul_f32_e32 v182, 0x45800000, v1
	v_cndmask_b32_e32 v194, v1, v182, vcc
	v_pk_mul_f32 v[182:183], v[52:53], v[194:195] op_sel_hi:[1,0]
	v_pk_mul_f32 v[50:51], v[50:51], v[194:195] op_sel_hi:[1,0]
	s_and_b64 vcc, exec, s[4:5]
	s_waitcnt vmcnt(6)
	v_pk_fma_f32 v[52:53], v[32:33], v[50:51], v[36:37]
	v_pk_fma_f32 v[50:51], v[30:31], v[182:183], v[34:35]
	s_mov_b64 s[28:29], -1
	s_cbranch_vccnz .LBB0_1324
	v_cvt_pk_f16_f32 v182, v50, v51
	v_cvt_pk_f16_f32 v183, v52, v53
	global_store_dwordx2 v[176:177], v[182:183], off nt
	v_pk_fma_f32 v[176:177], v[52:53], v[212:213], v[48:49]
	v_pk_fma_f32 v[182:183], v[50:51], v[210:211], v[46:47]
	s_mov_b64 s[28:29], 0
	v_cvt_pk_bf16_f32 v182, v182, v183
	v_cvt_pk_bf16_f32 v183, v176, v177
	v_lshl_add_u64 v[176:177], v[78:79], 0, s[22:23]
	global_store_dwordx2 v[176:177], v[182:183], off
